# v19: v15 plus software-pipelined LDS fragment reads (rotating register buffers, counted lgkmcnt) in the QK and PV sections of the MLA, window and selected attention loops
# baseline (speedup 1.0000x reference)
; DI void load_tile_k(int tid, const bf16_t* __restrict__ g, int ld, char* dst) { u32x4 r[4]; ldg_tile(tid, g, ld, r); sts_tile_k(tid, r, dst); }
; DI void load_tile_v(int tid, const bf16_t* __restrict__ g, int ld, char* dst) { u32x4 r[4]; ldg_tile(tid, g, ld, r); sts_tile_v(tid, r, dst); }
; template <int NKS, int QS>
; DI void qk_tile(const char* Ks, const bf16x8 (&qf)[QS][6], int ks0, f32x4 (&s)[4][QS], int lane) {
; #pragma unroll
;   for (int ks = 0; ks < NKS; ++ks)
; #pragma unroll
;     for (int kt = 0; kt < 4; ++kt) {
;       const bf16x8 kf = *(const bf16x8*)(Ks + koff(kt * 16 + (lane & 15), ks * 4 + (lane >> 4)));
; #pragma unroll
;       for (int qs = 0; qs < QS; ++qs) s[kt][qs] = __builtin_amdgcn_mfma_f32_16x16x32_bf16(kf, qf[qs][ks0 + ks], s[kt][qs], 0, 0, 0);
;     }
; }
; template <int QS>
; DI void nsa_cmpwin_item(int item, const bf16_t* __restrict__ z, const bf16_t* __restrict__ kcmp, const bf16_t* __restrict__ vcmp,
;                                 const float* __restrict__ bgate, float* __restrict__ P, float* __restrict__ part, char* smem) {
;     ...
;     for (int j = j0; j <= j1; ++j) {
;       __syncthreads();
;       load_tile_k(tid, z + (tb + j * 64) * NSP + NKW + grp * 128, NSP, Ks);
;       load_tile_v(tid, z + (tb + j * 64) * NSP + NVW + grp * 128, NSP, Vs);
;       __syncthreads();
;       f32x4 s[4][QS];
; #pragma unroll
;       for (int kt = 0; kt < 4; ++kt)
; #pragma unroll
;         for (int qs = 0; qs < QS; ++qs) s[kt][qs] = (f32x4){0.f, 0.f, 0.f, 0.f};
;       qk_tile<4, QS>(Ks, qf, 0, s, lane);
.LBB0_487:
	s_ashr_i32 s0, s11, 31
	s_add_u32 s1, s68, s11
	s_addc_u32 s0, s69, s0
	s_mulk_i32 s0, 0x2900
	s_mul_hi_u32 s4, s1, 0x2900
	s_add_i32 s4, s4, s0
	s_mulk_i32 s1, 0x2900
	s_add_u32 s0, s86, s1
	s_addc_u32 s1, s87, s4
	s_add_u32 s0, s0, s12
	s_addc_u32 s1, s1, 0
	v_lshl_add_u64 v[114:115], s[0:1], 0, v[0:1]
	s_mov_b64 s[0:1], 0x2000
	v_lshl_add_u64 v[110:111], v[114:115], 0, s[0:1]
	v_lshl_add_u64 v[98:99], v[110:111], 0, v[134:135]
	s_barrier
	global_load_dwordx4 v[98:101], v[98:99], off
	v_lshl_add_u64 v[102:103], v[110:111], 0, v[136:137]
	global_load_dwordx4 v[102:105], v[102:103], off
	v_lshl_add_u64 v[106:107], v[110:111], 0, v[146:147]
	global_load_dwordx4 v[106:109], v[106:107], off
	v_lshl_add_u64 v[110:111], v[110:111], 0, v[152:153]
	global_load_dwordx4 v[110:113], v[110:111], off
	s_mov_b64 s[0:1], 0x2400
	s_mov_b64 s[6:7], -1
	v_lshl_add_u64 v[158:159], v[114:115], 0, s[0:1]
	v_lshl_add_u64 v[116:117], v[158:159], 0, v[134:135]
	global_load_dwordx4 v[116:119], v[116:117], off
	v_lshl_add_u64 v[120:121], v[158:159], 0, v[136:137]
	global_load_dwordx4 v[120:123], v[120:121], off
	v_lshl_add_u64 v[124:125], v[158:159], 0, v[146:147]
	global_load_dwordx4 v[124:127], v[124:125], off
	v_lshl_add_u64 v[154:155], v[158:159], 0, v[152:153]
	global_load_dwordx4 v[154:157], v[154:155], off
	s_waitcnt vmcnt(7)
	ds_write_b128 v172, v[98:101]
	s_waitcnt vmcnt(6)
	ds_write_b128 v173, v[102:105]
	s_waitcnt vmcnt(5)
	ds_write_b128 v174, v[106:109]
	s_waitcnt vmcnt(4)
	ds_write_b128 v175, v[110:113]
	s_nop 0
	s_add_i32 s0, s11, 63
	s_cmp_le_i32 s0, s71
	s_cselect_b64 s[0:1], -1, 0
	s_cmp_gt_i32 s11, s9
	s_cselect_b64 s[4:5], -1, 0
	s_and_b64 s[4:5], s[0:1], s[4:5]
	s_and_b64 vcc, exec, s[4:5]
	s_waitcnt vmcnt(3)
	ds_write_b128 v176, v[116:119] offset:16384
	s_waitcnt vmcnt(2)
	ds_write_b128 v177, v[120:123] offset:16384
	s_waitcnt vmcnt(1)
	ds_write_b128 v178, v[124:127] offset:16384
	s_waitcnt vmcnt(0)
	ds_write_b128 v179, v[154:157] offset:16384
	s_waitcnt lgkmcnt(0)
	s_barrier
	ds_read_b128 v[156:159], v182
	ds_read_b128 v[160:163], v182 offset:4096
	ds_read_b128 v[232:235], v183
	ds_read_b128 v[236:239], v182 offset:8192
	ds_read_b128 v[240:243], v182 offset:12288
	s_waitcnt lgkmcnt(4)
	v_mfma_f32_16x16x32_bf16 v[126:129], v[156:159], v[2:5], 0
	v_mfma_f32_16x16x32_bf16 v[110:113], v[156:159], v[18:21], 0
	ds_read_b128 v[156:159], v183 offset:4096
	s_waitcnt lgkmcnt(4)
	v_mfma_f32_16x16x32_bf16 v[122:125], v[160:163], v[2:5], 0
	v_mfma_f32_16x16x32_bf16 v[106:109], v[160:163], v[18:21], 0
	ds_read_b128 v[160:163], v183 offset:8192
	s_waitcnt lgkmcnt(4)
	v_mfma_f32_16x16x32_bf16 v[126:129], v[232:235], v[6:9], v[126:129]
	v_mfma_f32_16x16x32_bf16 v[110:113], v[232:235], v[22:25], v[110:113]
	ds_read_b128 v[232:235], v183 offset:12288
	s_waitcnt lgkmcnt(4)
	v_mfma_f32_16x16x32_bf16 v[118:121], v[236:239], v[2:5], 0
	v_mfma_f32_16x16x32_bf16 v[102:105], v[236:239], v[18:21], 0
	ds_read_b128 v[236:239], v184
	s_waitcnt lgkmcnt(4)
	v_mfma_f32_16x16x32_bf16 v[114:117], v[240:243], v[2:5], 0
	v_mfma_f32_16x16x32_bf16 v[98:101], v[240:243], v[18:21], 0
	ds_read_b128 v[240:243], v184 offset:4096
	s_waitcnt lgkmcnt(4)
	v_mfma_f32_16x16x32_bf16 v[122:125], v[156:159], v[6:9], v[122:125]
	v_mfma_f32_16x16x32_bf16 v[106:109], v[156:159], v[22:25], v[106:109]
	ds_read_b128 v[156:159], v184 offset:8192
	s_waitcnt lgkmcnt(4)
	v_mfma_f32_16x16x32_bf16 v[118:121], v[160:163], v[6:9], v[118:121]
	v_mfma_f32_16x16x32_bf16 v[102:105], v[160:163], v[22:25], v[102:105]
	ds_read_b128 v[160:163], v184 offset:12288
	s_waitcnt lgkmcnt(4)
	v_mfma_f32_16x16x32_bf16 v[114:117], v[232:235], v[6:9], v[114:117]
	v_mfma_f32_16x16x32_bf16 v[98:101], v[232:235], v[22:25], v[98:101]
	ds_read_b128 v[232:235], v185
	s_waitcnt lgkmcnt(4)
	v_mfma_f32_16x16x32_bf16 v[126:129], v[236:239], v[10:13], v[126:129]
	v_mfma_f32_16x16x32_bf16 v[110:113], v[236:239], v[26:29], v[110:113]
	ds_read_b128 v[236:239], v185 offset:4096
	s_waitcnt lgkmcnt(4)
	v_mfma_f32_16x16x32_bf16 v[122:125], v[240:243], v[10:13], v[122:125]
	v_mfma_f32_16x16x32_bf16 v[106:109], v[240:243], v[26:29], v[106:109]
	ds_read_b128 v[240:243], v185 offset:8192
	s_waitcnt lgkmcnt(4)
	v_mfma_f32_16x16x32_bf16 v[118:121], v[156:159], v[10:13], v[118:121]
	v_mfma_f32_16x16x32_bf16 v[102:105], v[156:159], v[26:29], v[102:105]
	ds_read_b128 v[156:159], v185 offset:12288
	s_waitcnt lgkmcnt(4)
	v_mfma_f32_16x16x32_bf16 v[114:117], v[160:163], v[10:13], v[114:117]
	v_mfma_f32_16x16x32_bf16 v[98:101], v[160:163], v[26:29], v[98:101]
	s_waitcnt lgkmcnt(3)
	v_mfma_f32_16x16x32_bf16 v[126:129], v[232:235], v[14:17], v[126:129]
	v_mfma_f32_16x16x32_bf16 v[110:113], v[232:235], v[30:33], v[110:113]
	s_waitcnt lgkmcnt(2)
	v_mfma_f32_16x16x32_bf16 v[122:125], v[236:239], v[14:17], v[122:125]
	v_mfma_f32_16x16x32_bf16 v[106:109], v[236:239], v[30:33], v[106:109]
	s_waitcnt lgkmcnt(1)
	v_mfma_f32_16x16x32_bf16 v[118:121], v[240:243], v[14:17], v[118:121]
	v_mfma_f32_16x16x32_bf16 v[102:105], v[240:243], v[30:33], v[102:105]
	s_waitcnt lgkmcnt(0)
	v_mfma_f32_16x16x32_bf16 v[114:117], v[156:159], v[14:17], v[114:117]
	v_mfma_f32_16x16x32_bf16 v[98:101], v[156:159], v[30:33], v[98:101]
	v_add_u32_e32 v154, s11, v208
	v_cmp_le_i32_e64 s[0:1], v154, v142
	v_add_u32_e32 v224, 2, v154
	s_nop 7
	v_add_u32_e32 v221, 3, v154
	v_add_u32_e32 v222, 16, v154
	v_add_u32_e32 v218, 17, v154
	v_add_u32_e32 v216, 18, v154
	v_add_u32_e32 v228, 19, v154
	v_add_u32_e32 v227, 32, v154
	v_add_u32_e32 v226, 33, v154
	v_add_u32_e32 v225, 34, v154
	v_add_u32_e32 v223, 35, v154
	v_add_u32_e32 v220, 48, v154
	v_add_u32_e32 v219, 49, v154
	v_add_u32_e32 v217, 50, v154
	v_add_u32_e32 v215, 51, v154
	s_cbranch_vccnz .LBB0_489
; template <int MODE, int QS>
; DI void softmax_tile(f32x4 (&s)[4][QS], f32x4 (&o)[QS][8], float (&m)[QS], float (&l)[QS], const int (&qi)[QS], const unsigned (&qmask)[QS],
;                      int kbase, int tilebit, float sc, int lane, bool interior) {
;     ...
; #pragma unroll
;       for (int kt = 0; kt < 4; ++kt)
; #pragma unroll
;         for (int r = 0; r < 4; ++r) {
;           const int kj = kbase + kt * 16 + 4 * g + r;
;           bool v = kj <= qi[qs];
;           if (MODE == AM_WIN) v = v && (kj > qi[qs] - 512);
;           if (MODE == AM_SEL) v = v && ((qmask[qs] >> tilebit) & 1u);
;           const float x = v ? s[kt][qs][r] * sc : -1e30f;
;           s[kt][qs][r] = x;
;           mx = fmaxf(mx, x);
;         }
;     }
;     mx = fmaxf(mx, __shfl_xor(mx, 16)); mx = fmaxf(mx, __shfl_xor(mx, 32));
	v_cmp_gt_i32_e32 vcc, v154, v209
	v_mul_f32_e32 v155, 0x3e0293ee, v126
	s_and_b64 vcc, s[0:1], vcc
	v_cndmask_b32_e32 v156, v199, v155, vcc
	v_cmp_lt_i32_e32 vcc, v154, v142
	v_cmp_ge_i32_e64 s[0:1], v154, v209
	v_mul_f32_e32 v155, 0x3e0293ee, v127
	s_and_b64 vcc, vcc, s[0:1]
	v_cndmask_b32_e32 v157, v199, v155, vcc
	v_cmp_le_i32_e32 vcc, v224, v142
	v_cmp_gt_i32_e64 s[0:1], v224, v209
	v_mul_f32_e32 v158, 0x3e0293ee, v128
	s_and_b64 vcc, vcc, s[0:1]
	v_cndmask_b32_e32 v158, v199, v158, vcc
	v_cmp_le_i32_e32 vcc, v221, v142
	v_cmp_gt_i32_e64 s[0:1], v221, v209
	v_mul_f32_e32 v159, 0x3e0293ee, v129
	s_and_b64 vcc, vcc, s[0:1]
	v_cndmask_b32_e32 v159, v199, v159, vcc
	v_cmp_le_i32_e32 vcc, v222, v142
	v_cmp_gt_i32_e64 s[0:1], v222, v209
	v_mul_f32_e32 v160, 0x3e0293ee, v122
	s_and_b64 vcc, vcc, s[0:1]
	v_cndmask_b32_e32 v160, v199, v160, vcc
	v_cmp_le_i32_e32 vcc, v218, v142
	v_cmp_gt_i32_e64 s[0:1], v218, v209
	v_mul_f32_e32 v161, 0x3e0293ee, v123
	s_and_b64 vcc, vcc, s[0:1]
	v_cndmask_b32_e32 v161, v199, v161, vcc
	v_cmp_le_i32_e32 vcc, v216, v142
	v_cmp_gt_i32_e64 s[0:1], v216, v209
	v_mul_f32_e32 v162, 0x3e0293ee, v124
	s_and_b64 vcc, vcc, s[0:1]
	v_cndmask_b32_e32 v162, v199, v162, vcc
	v_cmp_le_i32_e32 vcc, v228, v142
	v_cmp_gt_i32_e64 s[0:1], v228, v209
	v_mul_f32_e32 v163, 0x3e0293ee, v125
	s_and_b64 vcc, vcc, s[0:1]
	v_cndmask_b32_e32 v163, v199, v163, vcc
	v_cmp_le_i32_e32 vcc, v227, v142
	v_cmp_gt_i32_e64 s[0:1], v227, v209
	v_mul_f32_e32 v164, 0x3e0293ee, v118
	s_and_b64 vcc, vcc, s[0:1]
	v_cndmask_b32_e32 v164, v199, v164, vcc
	v_cmp_le_i32_e32 vcc, v226, v142
	v_cmp_gt_i32_e64 s[0:1], v226, v209
	v_mul_f32_e32 v165, 0x3e0293ee, v119
	s_and_b64 vcc, vcc, s[0:1]
	v_cndmask_b32_e32 v165, v199, v165, vcc
	v_cmp_le_i32_e32 vcc, v225, v142
	v_cmp_gt_i32_e64 s[0:1], v225, v209
	v_mul_f32_e32 v166, 0x3e0293ee, v120
	s_and_b64 vcc, vcc, s[0:1]
	v_cndmask_b32_e32 v166, v199, v166, vcc
	v_cmp_le_i32_e32 vcc, v223, v142
	v_cmp_gt_i32_e64 s[0:1], v223, v209
	v_mul_f32_e32 v167, 0x3e0293ee, v121
	s_and_b64 vcc, vcc, s[0:1]
	v_cndmask_b32_e32 v167, v199, v167, vcc
	v_cmp_le_i32_e32 vcc, v220, v142
	v_cmp_gt_i32_e64 s[0:1], v220, v209
	v_mul_f32_e32 v168, 0x3e0293ee, v114
	s_and_b64 vcc, vcc, s[0:1]
	v_max3_f32 v155, v156, s83, v157
	v_cndmask_b32_e32 v168, v199, v168, vcc
	v_cmp_le_i32_e32 vcc, v219, v142
	v_cmp_gt_i32_e64 s[0:1], v219, v209
	v_max3_f32 v155, v155, v158, v159
	v_mul_f32_e32 v169, 0x3e0293ee, v115
	s_and_b64 vcc, vcc, s[0:1]
	v_max3_f32 v155, v155, v160, v161
	v_cndmask_b32_e32 v169, v199, v169, vcc
	v_cmp_le_i32_e32 vcc, v217, v142
	v_cmp_gt_i32_e64 s[0:1], v217, v209
	v_max3_f32 v155, v155, v162, v163
	v_mul_f32_e32 v170, 0x3e0293ee, v116
	s_and_b64 vcc, vcc, s[0:1]
	v_max3_f32 v155, v155, v164, v165
	v_cndmask_b32_e32 v170, v199, v170, vcc
	v_cmp_le_i32_e32 vcc, v215, v142
	v_cmp_gt_i32_e64 s[0:1], v215, v209
	v_max3_f32 v155, v155, v166, v167
	v_mul_f32_e32 v171, 0x3e0293ee, v117
	s_and_b64 vcc, vcc, s[0:1]
	v_max3_f32 v155, v155, v168, v169
	v_cndmask_b32_e32 v171, v199, v171, vcc
	v_max3_f32 v155, v155, v170, v171
	s_mov_b64 s[6:7], 0

; #define LDSP(T, p) ((__attribute__((address_space(3))) T*)(p))
; DI unsigned pack2(float lo, float hi) { unsigned r; asm("v_cvt_pk_bf16_f32 %0, %1, %2" : "=v"(r) : "v"(lo), "v"(hi)); return r; }
; template <int QS>
; DI void pv_tile(const char* Vs, const f32x4 (&s)[4][QS], f32x4 (&o)[QS][8], int lane) {
;   const int g = lane >> 4, i = lane & 15;
; #pragma unroll
;   for (int c = 0; c < 2; ++c) {
;     bf16x8 pf[QS];
; #pragma unroll
;     for (int qs = 0; qs < QS; ++qs) {
;       union { uint4 u; bf16x8 v; } cv;
;       cv.u.x = pack2(s[2 * c][qs][0], s[2 * c][qs][1]); cv.u.y = pack2(s[2 * c][qs][2], s[2 * c][qs][3]);
;       cv.u.z = pack2(s[2 * c + 1][qs][0], s[2 * c + 1][qs][1]); cv.u.w = pack2(s[2 * c + 1][qs][2], s[2 * c + 1][qs][3]);
;       pf[qs] = cv.v;
;     }
;     const int r1 = 32 * c + 4 * g + (i >> 2), r2 = r1 + 16;
; #pragma unroll
;     for (int dt = 0; dt < 8; ++dt) {
;       const s16x4 lo = __builtin_amdgcn_ds_read_tr16_b64_v4i16(LDSP(s16x4, Vs + r1 * 256 + ((dt ^ (r1 & 7)) << 5) + 8 * (i & 3)));
;       const s16x4 hi = __builtin_amdgcn_ds_read_tr16_b64_v4i16(LDSP(s16x4, Vs + r2 * 256 + ((dt ^ (r2 & 7)) << 5) + 8 * (i & 3)));
;       bf16x8 vf; vf[0] = lo[0]; vf[1] = lo[1]; vf[2] = lo[2]; vf[3] = lo[3]; vf[4] = hi[0]; vf[5] = hi[1]; vf[6] = hi[2]; vf[7] = hi[3];
; #pragma unroll
;       for (int qs = 0; qs < QS; ++qs) o[qs][dt] = __builtin_amdgcn_mfma_f32_16x16x32_bf16(vf, pf[qs], o[qs][dt], 0, 0, 0);
;     }
; template <int MODE, int QS>
; DI void softmax_tile(f32x4 (&s)[4][QS], f32x4 (&o)[QS][8], float (&m)[QS], float (&l)[QS], const int (&qi)[QS], const unsigned (&qmask)[QS],
;                      int kbase, int tilebit, float sc, int lane, bool interior) {
;     ...
;     mx = fmaxf(mx, __shfl_xor(mx, 16)); mx = fmaxf(mx, __shfl_xor(mx, 32));
;     const bool keep = __all(mx - m[qs] <= 23.0831f);
;     const float mn = keep ? m[qs] : fmaxf(m[qs], mx);
;     const float alpha = keep ? 1.f : __builtin_amdgcn_exp2f(m[qs] - mn);
;     m[qs] = mn;
;     const float mnc = fmaxf(mn, -1e20f);
;     float ps = 0.f;
; #pragma unroll
;     for (int kt = 0; kt < 4; ++kt)
; #pragma unroll
;       for (int r = 0; r < 4; ++r) { const float p = __builtin_amdgcn_exp2f(s[kt][qs][r] - mnc); s[kt][qs][r] = p; ps += p; }
;     l[qs] = l[qs] * alpha + ps;
;     if (!keep) {
; #pragma unroll
;       for (int dt = 0; dt < 8; ++dt) o[qs][dt] *= alpha;
;     }
.LBB0_499:
	v_max_f32_e32 v99, v106, v106
	v_max_f32_e32 v99, 0xe0ad78ec, v99
	v_sub_f32_e32 v100, v116, v99
	v_exp_f32_e32 v102, v100
	v_sub_f32_e32 v101, v117, v99
	v_exp_f32_e32 v103, v101
	v_sub_f32_e32 v101, v118, v99
	v_exp_f32_e32 v104, v101
	v_sub_f32_e32 v101, v119, v99
	v_exp_f32_e32 v105, v101
	v_sub_f32_e32 v101, v120, v99
	v_add_f32_e32 v100, 0, v102
	v_exp_f32_e32 v107, v101
	v_sub_f32_e32 v101, v121, v99
	v_add_f32_e32 v100, v103, v100
	v_exp_f32_e32 v108, v101
	v_sub_f32_e32 v101, v122, v99
	v_add_f32_e32 v100, v104, v100
	v_exp_f32_e32 v109, v101
	v_sub_f32_e32 v101, v123, v99
	v_add_f32_e32 v100, v105, v100
	v_exp_f32_e32 v110, v101
	v_sub_f32_e32 v101, v124, v99
	v_add_f32_e32 v100, v107, v100
	v_exp_f32_e32 v112, v101
	v_sub_f32_e32 v101, v125, v99
	v_add_f32_e32 v100, v108, v100
	v_exp_f32_e32 v113, v101
	v_sub_f32_e32 v101, v126, v99
	v_add_f32_e32 v100, v109, v100
	v_exp_f32_e32 v116, v101
	v_sub_f32_e32 v101, v127, v99
	v_add_f32_e32 v100, v110, v100
	v_exp_f32_e32 v117, v101
	v_sub_f32_e32 v101, v128, v99
	v_add_f32_e32 v100, v112, v100
	v_exp_f32_e32 v118, v101
	v_sub_f32_e32 v101, v129, v99
	v_add_f32_e32 v100, v113, v100
	v_exp_f32_e32 v119, v101
	v_sub_f32_e32 v101, v154, v99
	v_add_f32_e32 v100, v116, v100
	v_exp_f32_e32 v120, v101
	v_sub_f32_e32 v99, v155, v99
	v_add_f32_e32 v100, v117, v100
	v_exp_f32_e32 v121, v99
	v_add_f32_e32 v100, v118, v100
	v_add_f32_e32 v100, v119, v100
	v_add_f32_e32 v100, v120, v100
	v_add_f32_e32 v154, v121, v100
	v_cndmask_b32_e64 v98, v98, 1.0, s[0:1]
	v_fmac_f32_e32 v154, v212, v98
	v_max_f32_e32 v98, v115, v115
	v_max_f32_e32 v98, 0xe0ad78ec, v98
	v_sub_f32_e32 v99, v156, v98
	v_exp_f32_e32 v99, v99
	v_sub_f32_e32 v101, v157, v98
	v_exp_f32_e32 v101, v101
	v_sub_f32_e32 v111, v158, v98
	v_exp_f32_e32 v111, v111
	v_sub_f32_e32 v122, v159, v98
	v_exp_f32_e32 v122, v122
	v_sub_f32_e32 v123, v160, v98
	v_add_f32_e32 v100, 0, v99
	v_exp_f32_e32 v123, v123
	v_sub_f32_e32 v124, v161, v98
	v_add_f32_e32 v100, v101, v100
	v_exp_f32_e32 v124, v124
	v_sub_f32_e32 v125, v162, v98
	v_add_f32_e32 v100, v111, v100
	v_exp_f32_e32 v125, v125
	v_sub_f32_e32 v126, v163, v98
	v_add_f32_e32 v100, v122, v100
	v_exp_f32_e32 v126, v126
	v_sub_f32_e32 v127, v164, v98
	v_add_f32_e32 v100, v123, v100
	v_exp_f32_e32 v127, v127
	v_sub_f32_e32 v128, v165, v98
	v_add_f32_e32 v100, v124, v100
	v_exp_f32_e32 v128, v128
	v_sub_f32_e32 v129, v166, v98
	v_add_f32_e32 v100, v125, v100
	v_exp_f32_e32 v129, v129
	v_sub_f32_e32 v155, v167, v98
	v_add_f32_e32 v100, v126, v100
	v_exp_f32_e32 v156, v155
	v_sub_f32_e32 v155, v168, v98
	v_add_f32_e32 v100, v127, v100
	v_exp_f32_e32 v157, v155
	v_sub_f32_e32 v155, v169, v98
	v_add_f32_e32 v100, v128, v100
	v_exp_f32_e32 v158, v155
	v_sub_f32_e32 v155, v170, v98
	v_add_f32_e32 v100, v129, v100
	v_exp_f32_e32 v159, v155
	v_sub_f32_e32 v98, v171, v98
	v_add_f32_e32 v100, v156, v100
	v_exp_f32_e32 v160, v98
	v_add_f32_e32 v100, v157, v100
	v_add_f32_e32 v100, v158, v100
	v_add_f32_e32 v100, v159, v100
	v_add_f32_e32 v155, v160, v100
	v_cndmask_b32_e64 v98, v114, 1.0, s[6:7]
	v_cvt_pk_bf16_f32 v102, v102, v103
	v_cvt_pk_bf16_f32 v103, v104, v105
	v_cvt_pk_bf16_f32 v104, v107, v108
	v_add_u32_e32 v107, v143, v145
	v_fmac_f32_e32 v155, v211, v98
	v_cvt_pk_bf16_f32 v98, v99, v101
	v_cvt_pk_bf16_f32 v99, v111, v122
	v_cvt_pk_bf16_f32 v105, v109, v110
	v_add_u32_e32 v211, v143, v145
	v_add_u32_e32 v212, v143, v186
	v_add_u32_e32 v213, v143, v187
	v_add_u32_e32 v214, v143, v188
	v_add_u32_e32 v215, v143, v189
	v_add_u32_e32 v216, v143, v205
	v_add_u32_e32 v217, v143, v206
	v_add_u32_e32 v218, v143, v207
	ds_read_b64_tr_b16 v[108:109], v211 offset:16384
	ds_read_b64_tr_b16 v[110:111], v211 offset:20480
	ds_read_b64_tr_b16 v[220:221], v212 offset:16384
	ds_read_b64_tr_b16 v[222:223], v212 offset:20480
	ds_read_b64_tr_b16 v[224:225], v213 offset:16384
	ds_read_b64_tr_b16 v[226:227], v213 offset:20480
	ds_read_b64_tr_b16 v[232:233], v214 offset:16384
	ds_read_b64_tr_b16 v[234:235], v214 offset:20480
	ds_read_b64_tr_b16 v[236:237], v215 offset:16384
	ds_read_b64_tr_b16 v[238:239], v215 offset:20480
	ds_read_b64_tr_b16 v[240:241], v216 offset:16384
	ds_read_b64_tr_b16 v[242:243], v216 offset:20480
	v_add_u32_e32 v114, v143, v186
	v_cvt_pk_bf16_f32 v100, v123, v124
	v_cvt_pk_bf16_f32 v101, v125, v126
	s_waitcnt lgkmcnt(10)
; #define LDSP(T, p) ((__attribute__((address_space(3))) T*)(p))
; DI unsigned pack2(float lo, float hi) { unsigned r; asm("v_cvt_pk_bf16_f32 %0, %1, %2" : "=v"(r) : "v"(lo), "v"(hi)); return r; }
; template <int QS>
; DI void pv_tile(const char* Vs, const f32x4 (&s)[4][QS], f32x4 (&o)[QS][8], int lane) {
;   const int g = lane >> 4, i = lane & 15;
; #pragma unroll
;   for (int c = 0; c < 2; ++c) {
;     bf16x8 pf[QS];
; #pragma unroll
;     for (int qs = 0; qs < QS; ++qs) {
;       union { uint4 u; bf16x8 v; } cv;
;       cv.u.x = pack2(s[2 * c][qs][0], s[2 * c][qs][1]); cv.u.y = pack2(s[2 * c][qs][2], s[2 * c][qs][3]);
;       cv.u.z = pack2(s[2 * c + 1][qs][0], s[2 * c + 1][qs][1]); cv.u.w = pack2(s[2 * c + 1][qs][2], s[2 * c + 1][qs][3]);
;       pf[qs] = cv.v;
;     }
;     const int r1 = 32 * c + 4 * g + (i >> 2), r2 = r1 + 16;
; #pragma unroll
;     for (int dt = 0; dt < 8; ++dt) {
;       const s16x4 lo = __builtin_amdgcn_ds_read_tr16_b64_v4i16(LDSP(s16x4, Vs + r1 * 256 + ((dt ^ (r1 & 7)) << 5) + 8 * (i & 3)));
;       const s16x4 hi = __builtin_amdgcn_ds_read_tr16_b64_v4i16(LDSP(s16x4, Vs + r2 * 256 + ((dt ^ (r2 & 7)) << 5) + 8 * (i & 3)));
;       bf16x8 vf; vf[0] = lo[0]; vf[1] = lo[1]; vf[2] = lo[2]; vf[3] = lo[3]; vf[4] = hi[0]; vf[5] = hi[1]; vf[6] = hi[2]; vf[7] = hi[3];
; #pragma unroll
;       for (int qs = 0; qs < QS; ++qs) o[qs][dt] = __builtin_amdgcn_mfma_f32_16x16x32_bf16(vf, pf[qs], o[qs][dt], 0, 0, 0);
;     }
	v_mfma_f32_16x16x32_bf16 v[46:49], v[108:111], v[102:105], v[46:49]
	v_add_u32_e32 v122, v143, v187
	v_add_u32_e32 v123, v143, v188
	v_add_u32_e32 v124, v143, v189
	v_mfma_f32_16x16x32_bf16 v[66:69], v[108:111], v[98:101], v[66:69]
	ds_read_b64_tr_b16 v[108:109], v217 offset:16384
	ds_read_b64_tr_b16 v[110:111], v217 offset:20480
	v_add_u32_e32 v125, v143, v205
	v_add_u32_e32 v126, v143, v206
	s_waitcnt lgkmcnt(10)
	v_mfma_f32_16x16x32_bf16 v[70:73], v[220:223], v[98:101], v[70:73]
	v_add_u32_e32 v161, v143, v207
	s_add_i32 s10, s10, 1
	s_add_i32 s11, s11, 64
	v_mfma_f32_16x16x32_bf16 v[38:41], v[220:223], v[102:105], v[38:41]
	ds_read_b64_tr_b16 v[220:221], v218 offset:16384
	ds_read_b64_tr_b16 v[222:223], v218 offset:20480
	s_cmp_gt_i32 s10, s8
	s_waitcnt lgkmcnt(10)
	v_mfma_f32_16x16x32_bf16 v[74:77], v[224:227], v[98:101], v[74:77]
	v_mfma_f32_16x16x32_bf16 v[42:45], v[224:227], v[102:105], v[42:45]
	ds_read_b64_tr_b16 v[224:225], v211 offset:24576
	ds_read_b64_tr_b16 v[226:227], v211 offset:28672
	s_waitcnt lgkmcnt(10)
	v_mfma_f32_16x16x32_bf16 v[78:81], v[232:235], v[98:101], v[78:81]
	v_mfma_f32_16x16x32_bf16 v[50:53], v[232:235], v[102:105], v[50:53]
	ds_read_b64_tr_b16 v[232:233], v212 offset:24576
	ds_read_b64_tr_b16 v[234:235], v212 offset:28672
	s_waitcnt lgkmcnt(10)
	v_mfma_f32_16x16x32_bf16 v[82:85], v[236:239], v[98:101], v[82:85]
	v_mfma_f32_16x16x32_bf16 v[54:57], v[236:239], v[102:105], v[54:57]
	ds_read_b64_tr_b16 v[236:237], v213 offset:24576
	ds_read_b64_tr_b16 v[238:239], v213 offset:28672
	s_waitcnt lgkmcnt(10)
	v_mfma_f32_16x16x32_bf16 v[86:89], v[240:243], v[98:101], v[86:89]
	v_mfma_f32_16x16x32_bf16 v[58:61], v[240:243], v[102:105], v[58:61]
	ds_read_b64_tr_b16 v[240:241], v214 offset:24576
	ds_read_b64_tr_b16 v[242:243], v214 offset:28672
	s_waitcnt lgkmcnt(10)
	v_mfma_f32_16x16x32_bf16 v[90:93], v[108:111], v[98:101], v[90:93]
	v_mfma_f32_16x16x32_bf16 v[62:65], v[108:111], v[102:105], v[62:65]
	ds_read_b64_tr_b16 v[108:109], v215 offset:24576
	ds_read_b64_tr_b16 v[110:111], v215 offset:28672
	s_waitcnt lgkmcnt(10)
	v_mfma_f32_16x16x32_bf16 v[94:97], v[220:223], v[98:101], v[94:97]
	v_cvt_pk_bf16_f32 v98, v127, v128
	v_cvt_pk_bf16_f32 v99, v129, v156
	v_cvt_pk_bf16_f32 v100, v157, v158
	v_mfma_f32_16x16x32_bf16 v[34:37], v[220:223], v[102:105], v[34:37]
	ds_read_b64_tr_b16 v[220:221], v216 offset:24576
	ds_read_b64_tr_b16 v[222:223], v216 offset:28672
	v_cvt_pk_bf16_f32 v101, v159, v160
	v_cvt_pk_bf16_f32 v102, v112, v113
	v_cvt_pk_bf16_f32 v103, v116, v117
	v_cvt_pk_bf16_f32 v104, v118, v119
	v_cvt_pk_bf16_f32 v105, v120, v121
	s_waitcnt lgkmcnt(10)
	v_mfma_f32_16x16x32_bf16 v[66:69], v[224:227], v[98:101], v[66:69]
	v_mfma_f32_16x16x32_bf16 v[46:49], v[224:227], v[102:105], v[46:49]
	ds_read_b64_tr_b16 v[224:225], v217 offset:24576
	ds_read_b64_tr_b16 v[226:227], v217 offset:28672
	s_waitcnt lgkmcnt(10)
	v_mfma_f32_16x16x32_bf16 v[70:73], v[232:235], v[98:101], v[70:73]
	v_mfma_f32_16x16x32_bf16 v[38:41], v[232:235], v[102:105], v[38:41]
	ds_read_b64_tr_b16 v[232:233], v218 offset:24576
	ds_read_b64_tr_b16 v[234:235], v218 offset:28672
	s_waitcnt lgkmcnt(10)
	v_mfma_f32_16x16x32_bf16 v[74:77], v[236:239], v[98:101], v[74:77]
	v_mfma_f32_16x16x32_bf16 v[42:45], v[236:239], v[102:105], v[42:45]
	s_waitcnt lgkmcnt(8)
	v_mfma_f32_16x16x32_bf16 v[78:81], v[240:243], v[98:101], v[78:81]
	v_mfma_f32_16x16x32_bf16 v[50:53], v[240:243], v[102:105], v[50:53]
	s_waitcnt lgkmcnt(6)
	v_mfma_f32_16x16x32_bf16 v[82:85], v[108:111], v[98:101], v[82:85]
	v_mfma_f32_16x16x32_bf16 v[54:57], v[108:111], v[102:105], v[54:57]
	s_waitcnt lgkmcnt(4)
	v_mfma_f32_16x16x32_bf16 v[86:89], v[220:223], v[98:101], v[86:89]
	v_mfma_f32_16x16x32_bf16 v[58:61], v[220:223], v[102:105], v[58:61]
	s_waitcnt lgkmcnt(2)
	v_mfma_f32_16x16x32_bf16 v[90:93], v[224:227], v[98:101], v[90:93]
	v_mfma_f32_16x16x32_bf16 v[62:65], v[224:227], v[102:105], v[62:65]
	s_waitcnt lgkmcnt(0)
	v_mfma_f32_16x16x32_bf16 v[94:97], v[232:235], v[98:101], v[94:97]
	v_mfma_f32_16x16x32_bf16 v[34:37], v[232:235], v[102:105], v[34:37]
	s_cbranch_scc1 .LBB0_483
	v_mov_b32_e32 v213, v106
	v_mov_b32_e32 v214, v115
	v_mov_b32_e32 v212, v154
	v_mov_b32_e32 v211, v155
	s_branch .LBB0_487

; DI void load_tile_k(int tid, const bf16_t* __restrict__ g, int ld, char* dst) { u32x4 r[4]; ldg_tile(tid, g, ld, r); sts_tile_k(tid, r, dst); }
; DI void load_tile_v(int tid, const bf16_t* __restrict__ g, int ld, char* dst) { u32x4 r[4]; ldg_tile(tid, g, ld, r); sts_tile_v(tid, r, dst); }
; template <int NKS, int QS>
; DI void qk_tile(const char* Ks, const bf16x8 (&qf)[QS][6], int ks0, f32x4 (&s)[4][QS], int lane) {
; #pragma unroll
;   for (int ks = 0; ks < NKS; ++ks)
; #pragma unroll
;     for (int kt = 0; kt < 4; ++kt) {
;       const bf16x8 kf = *(const bf16x8*)(Ks + koff(kt * 16 + (lane & 15), ks * 4 + (lane >> 4)));
; #pragma unroll
;       for (int qs = 0; qs < QS; ++qs) s[kt][qs] = __builtin_amdgcn_mfma_f32_16x16x32_bf16(kf, qf[qs][ks0 + ks], s[kt][qs], 0, 0, 0);
;     }
; }
; template <int QS>
; DI void nsa_sel_item(int item, const bf16_t* __restrict__ z, const unsigned* __restrict__ sel, const float* __restrict__ bgate,
;                              const float* __restrict__ part, bf16_t* __restrict__ mix, char* smem) {
;     ...
;   while (rem) {
;     const int j = __builtin_ctz(rem);
;     rem &= rem - 1u;
;     __syncthreads();
;     load_tile_k(tid, z + (tb + j * 64) * NSP + NKS + grp * 128, NSP, Ks);
;     load_tile_v(tid, z + (tb + j * 64) * NSP + NVS + grp * 128, NSP, Vs);
;     __syncthreads();
;     f32x4 s[4][QS];
; #pragma unroll
;     for (int kt = 0; kt < 4; ++kt)
; #pragma unroll
;       for (int qs = 0; qs < QS; ++qs) s[kt][qs] = (f32x4){0.f, 0.f, 0.f, 0.f};
;     qk_tile<4, QS>(Ks, qf, 0, s, lane);
.LBB0_616:
	s_ff1_i32_b32 s0, s30
	s_lshl_b32 s4, s0, 6
	s_or_b32 s1, s4, s96
	s_mulk_i32 s1, 0x2900
	s_add_u32 s1, s86, s1
	s_addc_u32 s3, s87, 0
	s_add_u32 s2, s1, s31
	s_addc_u32 s3, s3, 0
	v_lshl_add_u64 v[114:115], s[2:3], 0, v[0:1]
	s_mov_b64 s[2:3], 0x1800
	v_lshl_add_u64 v[110:111], v[114:115], 0, s[2:3]
	v_lshl_add_u64 v[98:99], v[110:111], 0, v[138:139]
	s_barrier
	global_load_dwordx4 v[98:101], v[98:99], off
	v_lshl_add_u64 v[102:103], v[110:111], 0, v[140:141]
	global_load_dwordx4 v[102:105], v[102:103], off
	v_lshl_add_u64 v[106:107], v[110:111], 0, v[142:143]
	global_load_dwordx4 v[106:109], v[106:107], off
	v_lshl_add_u64 v[110:111], v[110:111], 0, v[144:145]
	global_load_dwordx4 v[110:113], v[110:111], off
	s_mov_b64 s[2:3], 0x1c00
	v_lshl_add_u64 v[158:159], v[114:115], 0, s[2:3]
	v_lshl_add_u64 v[116:117], v[158:159], 0, v[138:139]
	global_load_dwordx4 v[116:119], v[116:117], off
	v_lshl_add_u64 v[120:121], v[158:159], 0, v[140:141]
	global_load_dwordx4 v[120:123], v[120:121], off
	v_lshl_add_u64 v[124:125], v[158:159], 0, v[142:143]
	global_load_dwordx4 v[124:127], v[124:125], off
	v_lshl_add_u64 v[152:153], v[158:159], 0, v[144:145]
	global_load_dwordx4 v[152:155], v[152:153], off
	s_or_b32 s1, s4, 63
	s_cmp_le_i32 s1, s29
	s_cselect_b64 s[24:25], -1, 0
	s_lshl_b32 s33, 1, s0
	v_and_b32_e32 v167, s33, v172
	s_and_b64 vcc, exec, s[24:25]
	v_cmp_eq_u32_e64 s[0:1], 0, v167
	s_waitcnt vmcnt(7)
	ds_write_b128 v179, v[98:101]
	s_waitcnt vmcnt(6)
	ds_write_b128 v180, v[102:105]
	s_waitcnt vmcnt(5)
	ds_write_b128 v181, v[106:109]
	s_waitcnt vmcnt(4)
	ds_write_b128 v182, v[110:113]
	s_nop 0
	s_mov_b64 s[2:3], -1
	s_waitcnt vmcnt(3)
	ds_write_b128 v183, v[116:119] offset:16384
	s_waitcnt vmcnt(2)
	ds_write_b128 v184, v[120:123] offset:16384
	s_waitcnt vmcnt(1)
	ds_write_b128 v185, v[124:127] offset:16384
	s_waitcnt vmcnt(0)
	ds_write_b128 v186, v[152:155] offset:16384
	s_waitcnt lgkmcnt(0)
	s_barrier
	ds_read_b128 v[152:155], v187
	ds_read_b128 v[156:159], v187 offset:4096
	ds_read_b128 v[160:163], v188
	ds_read_b128 v[232:235], v187 offset:8192
	ds_read_b128 v[236:239], v187 offset:12288
	ds_read_b128 v[240:243], v188 offset:4096
	s_waitcnt lgkmcnt(5)
	v_mfma_f32_16x16x32_bf16 v[126:129], v[152:155], v[62:65], 0
	v_mfma_f32_16x16x32_bf16 v[110:113], v[152:155], v[78:81], 0
	ds_read_b128 v[152:155], v188 offset:8192
	s_waitcnt lgkmcnt(5)
	v_mfma_f32_16x16x32_bf16 v[122:125], v[156:159], v[62:65], 0
	v_mfma_f32_16x16x32_bf16 v[106:109], v[156:159], v[78:81], 0
	ds_read_b128 v[156:159], v188 offset:12288
	s_waitcnt lgkmcnt(5)
	v_mfma_f32_16x16x32_bf16 v[126:129], v[160:163], v[66:69], v[126:129]
	v_mfma_f32_16x16x32_bf16 v[110:113], v[160:163], v[82:85], v[110:113]
	ds_read_b128 v[160:163], v189
	s_waitcnt lgkmcnt(5)
	v_mfma_f32_16x16x32_bf16 v[118:121], v[232:235], v[62:65], 0
	v_mfma_f32_16x16x32_bf16 v[102:105], v[232:235], v[78:81], 0
	ds_read_b128 v[232:235], v189 offset:4096
	s_waitcnt lgkmcnt(5)
	v_mfma_f32_16x16x32_bf16 v[114:117], v[236:239], v[62:65], 0
	v_mfma_f32_16x16x32_bf16 v[98:101], v[236:239], v[78:81], 0
	ds_read_b128 v[236:239], v189 offset:8192
	s_waitcnt lgkmcnt(5)
	v_mfma_f32_16x16x32_bf16 v[122:125], v[240:243], v[66:69], v[122:125]
	v_mfma_f32_16x16x32_bf16 v[106:109], v[240:243], v[82:85], v[106:109]
	ds_read_b128 v[240:243], v189 offset:12288
	s_waitcnt lgkmcnt(5)
	v_mfma_f32_16x16x32_bf16 v[118:121], v[152:155], v[66:69], v[118:121]
	v_mfma_f32_16x16x32_bf16 v[102:105], v[152:155], v[82:85], v[102:105]
	ds_read_b128 v[152:155], v205
	s_waitcnt lgkmcnt(5)
	v_mfma_f32_16x16x32_bf16 v[114:117], v[156:159], v[66:69], v[114:117]
	v_mfma_f32_16x16x32_bf16 v[98:101], v[156:159], v[82:85], v[98:101]
	ds_read_b128 v[156:159], v205 offset:4096
	s_waitcnt lgkmcnt(5)
	v_mfma_f32_16x16x32_bf16 v[126:129], v[160:163], v[70:73], v[126:129]
	v_mfma_f32_16x16x32_bf16 v[110:113], v[160:163], v[86:89], v[110:113]
	ds_read_b128 v[160:163], v205 offset:8192
	s_waitcnt lgkmcnt(5)
	v_mfma_f32_16x16x32_bf16 v[122:125], v[232:235], v[70:73], v[122:125]
	v_mfma_f32_16x16x32_bf16 v[106:109], v[232:235], v[86:89], v[106:109]
	ds_read_b128 v[232:235], v205 offset:12288
	s_waitcnt lgkmcnt(5)
	v_mfma_f32_16x16x32_bf16 v[118:121], v[236:239], v[70:73], v[118:121]
	v_mfma_f32_16x16x32_bf16 v[102:105], v[236:239], v[86:89], v[102:105]
	s_waitcnt lgkmcnt(4)
	v_mfma_f32_16x16x32_bf16 v[114:117], v[240:243], v[70:73], v[114:117]
	v_mfma_f32_16x16x32_bf16 v[98:101], v[240:243], v[86:89], v[98:101]
	s_waitcnt lgkmcnt(3)
	v_mfma_f32_16x16x32_bf16 v[126:129], v[152:155], v[74:77], v[126:129]
	v_mfma_f32_16x16x32_bf16 v[110:113], v[152:155], v[90:93], v[110:113]
	s_waitcnt lgkmcnt(2)
	v_mfma_f32_16x16x32_bf16 v[122:125], v[156:159], v[74:77], v[122:125]
	v_mfma_f32_16x16x32_bf16 v[106:109], v[156:159], v[90:93], v[106:109]
	s_waitcnt lgkmcnt(1)
	v_mfma_f32_16x16x32_bf16 v[118:121], v[160:163], v[74:77], v[118:121]
	v_mfma_f32_16x16x32_bf16 v[102:105], v[160:163], v[90:93], v[102:105]
	s_waitcnt lgkmcnt(0)
	v_mfma_f32_16x16x32_bf16 v[114:117], v[232:235], v[74:77], v[114:117]
	v_mfma_f32_16x16x32_bf16 v[98:101], v[232:235], v[90:93], v[98:101]
	s_nop 7
	s_cbranch_vccz .LBB0_618
	v_cndmask_b32_e64 v164, v201, 0, s[0:1]
	v_cndmask_b32_e64 v218, 0, v199, s[0:1]
	v_pk_fma_f32 v[152:153], v[126:127], v[164:165], v[218:219] op_sel_hi:[1,0,0]
	v_pk_fma_f32 v[146:147], v[128:129], v[164:165], v[218:219] op_sel_hi:[1,0,0]
	v_max3_f32 v154, v152, s83, v153
	v_max3_f32 v154, v154, v146, v147
	v_pk_fma_f32 v[156:157], v[122:123], v[164:165], v[218:219] op_sel_hi:[1,0,0]
	s_mov_b64 s[2:3], 0
	v_max3_f32 v158, v154, v156, v157
	v_pk_fma_f32 v[154:155], v[124:125], v[164:165], v[218:219] op_sel_hi:[1,0,0]
	s_nop 0
	v_max3_f32 v160, v158, v154, v155
	v_pk_fma_f32 v[158:159], v[118:119], v[164:165], v[218:219] op_sel_hi:[1,0,0]
	s_nop 0
	v_max3_f32 v162, v160, v158, v159
	v_pk_fma_f32 v[160:161], v[120:121], v[164:165], v[218:219] op_sel_hi:[1,0,0]
	s_nop 0
	v_max3_f32 v165, v162, v160, v161
	v_pk_fma_f32 v[162:163], v[114:115], v[164:165], v[218:219] op_sel_hi:[1,0,0]
	s_nop 0
	v_max3_f32 v217, v165, v162, v163
	v_pk_fma_f32 v[164:165], v[116:117], v[164:165], v[218:219] op_sel_hi:[1,0,0]
	s_nop 0
	v_max3_f32 v228, v217, v164, v165

; #define LDSP(T, p) ((__attribute__((address_space(3))) T*)(p))
; DI unsigned pack2(float lo, float hi) { unsigned r; asm("v_cvt_pk_bf16_f32 %0, %1, %2" : "=v"(r) : "v"(lo), "v"(hi)); return r; }
; template <int QS>
; DI void pv_tile(const char* Vs, const f32x4 (&s)[4][QS], f32x4 (&o)[QS][8], int lane) {
;   const int g = lane >> 4, i = lane & 15;
; #pragma unroll
;   for (int c = 0; c < 2; ++c) {
;     bf16x8 pf[QS];
; #pragma unroll
;     for (int qs = 0; qs < QS; ++qs) {
;       union { uint4 u; bf16x8 v; } cv;
;       cv.u.x = pack2(s[2 * c][qs][0], s[2 * c][qs][1]); cv.u.y = pack2(s[2 * c][qs][2], s[2 * c][qs][3]);
;       cv.u.z = pack2(s[2 * c + 1][qs][0], s[2 * c + 1][qs][1]); cv.u.w = pack2(s[2 * c + 1][qs][2], s[2 * c + 1][qs][3]);
;       pf[qs] = cv.v;
;     }
;     const int r1 = 32 * c + 4 * g + (i >> 2), r2 = r1 + 16;
; #pragma unroll
;     for (int dt = 0; dt < 8; ++dt) {
;       const s16x4 lo = __builtin_amdgcn_ds_read_tr16_b64_v4i16(LDSP(s16x4, Vs + r1 * 256 + ((dt ^ (r1 & 7)) << 5) + 8 * (i & 3)));
;       const s16x4 hi = __builtin_amdgcn_ds_read_tr16_b64_v4i16(LDSP(s16x4, Vs + r2 * 256 + ((dt ^ (r2 & 7)) << 5) + 8 * (i & 3)));
;       bf16x8 vf; vf[0] = lo[0]; vf[1] = lo[1]; vf[2] = lo[2]; vf[3] = lo[3]; vf[4] = hi[0]; vf[5] = hi[1]; vf[6] = hi[2]; vf[7] = hi[3];
; #pragma unroll
;       for (int qs = 0; qs < QS; ++qs) o[qs][dt] = __builtin_amdgcn_mfma_f32_16x16x32_bf16(vf, pf[qs], o[qs][dt], 0, 0, 0);
;     }
; template <int MODE, int QS>
; DI void softmax_tile(f32x4 (&s)[4][QS], f32x4 (&o)[QS][8], float (&m)[QS], float (&l)[QS], const int (&qi)[QS], const unsigned (&qmask)[QS],
;                      int kbase, int tilebit, float sc, int lane, bool interior) {
;     ...
;     mx = fmaxf(mx, __shfl_xor(mx, 16)); mx = fmaxf(mx, __shfl_xor(mx, 32));
;     const bool keep = __all(mx - m[qs] <= 23.0831f);
;     const float mn = keep ? m[qs] : fmaxf(m[qs], mx);
;     const float alpha = keep ? 1.f : __builtin_amdgcn_exp2f(m[qs] - mn);
;     m[qs] = mn;
;     const float mnc = fmaxf(mn, -1e20f);
;     float ps = 0.f;
; #pragma unroll
;     for (int kt = 0; kt < 4; ++kt)
; #pragma unroll
;       for (int r = 0; r < 4; ++r) { const float p = __builtin_amdgcn_exp2f(s[kt][qs][r] - mnc); s[kt][qs][r] = p; ps += p; }
;     l[qs] = l[qs] * alpha + ps;
;     if (!keep) {
; #pragma unroll
;       for (int dt = 0; dt < 8; ++dt) o[qs][dt] *= alpha;
;     }
.LBB0_628:
	v_max_f32_e32 v99, v108, v108
	v_max_f32_e32 v99, 0xe0ad78ec, v99
	v_sub_f32_e32 v100, v118, v99
	v_exp_f32_e32 v102, v100
	v_sub_f32_e32 v101, v119, v99
	v_exp_f32_e32 v103, v101
	v_sub_f32_e32 v101, v116, v99
	v_exp_f32_e32 v104, v101
	v_sub_f32_e32 v101, v117, v99
	v_exp_f32_e32 v105, v101
	v_sub_f32_e32 v101, v120, v99
	v_add_f32_e32 v100, 0, v102
	v_exp_f32_e32 v109, v101
	v_sub_f32_e32 v101, v121, v99
	v_add_f32_e32 v100, v103, v100
	v_exp_f32_e32 v110, v101
	v_sub_f32_e32 v101, v122, v99
	v_add_f32_e32 v100, v104, v100
	v_exp_f32_e32 v111, v101
	v_sub_f32_e32 v101, v123, v99
	v_add_f32_e32 v100, v105, v100
	v_exp_f32_e32 v112, v101
	v_sub_f32_e32 v101, v124, v99
	v_add_f32_e32 v100, v109, v100
	v_exp_f32_e32 v116, v101
	v_sub_f32_e32 v101, v125, v99
	v_add_f32_e32 v100, v110, v100
	v_exp_f32_e32 v117, v101
	v_sub_f32_e32 v101, v126, v99
	v_add_f32_e32 v100, v111, v100
	v_exp_f32_e32 v118, v101
	v_sub_f32_e32 v101, v127, v99
	v_add_f32_e32 v100, v112, v100
	v_exp_f32_e32 v119, v101
	v_sub_f32_e32 v101, v128, v99
	v_add_f32_e32 v100, v116, v100
	v_exp_f32_e32 v120, v101
	v_sub_f32_e32 v101, v129, v99
	v_add_f32_e32 v100, v117, v100
	v_exp_f32_e32 v121, v101
	v_sub_f32_e32 v101, v166, v99
	v_add_f32_e32 v100, v118, v100
	v_exp_f32_e32 v122, v101
	v_sub_f32_e32 v99, v167, v99
	v_add_f32_e32 v100, v119, v100
	v_exp_f32_e32 v123, v99
	v_add_f32_e32 v100, v120, v100
	v_add_f32_e32 v100, v121, v100
	v_add_f32_e32 v100, v122, v100
	v_add_f32_e32 v106, v123, v100
	v_cndmask_b32_e64 v98, v98, 1.0, s[0:1]
	v_fmac_f32_e32 v106, v215, v98
	v_max_f32_e32 v98, v115, v115
	v_max_f32_e32 v98, 0xe0ad78ec, v98
	v_sub_f32_e32 v99, v152, v98
	v_exp_f32_e32 v99, v99
	v_sub_f32_e32 v101, v153, v98
	v_exp_f32_e32 v101, v101
	v_sub_f32_e32 v107, v146, v98
	v_exp_f32_e32 v113, v107
	v_sub_f32_e32 v107, v147, v98
	v_exp_f32_e32 v124, v107
	v_sub_f32_e32 v107, v156, v98
	v_add_f32_e32 v100, 0, v99
	v_exp_f32_e32 v125, v107
	v_sub_f32_e32 v107, v157, v98
	v_add_f32_e32 v100, v101, v100
	v_exp_f32_e32 v126, v107
	v_sub_f32_e32 v107, v154, v98
	v_add_f32_e32 v100, v113, v100
	v_exp_f32_e32 v127, v107
	v_sub_f32_e32 v107, v155, v98
	v_add_f32_e32 v100, v124, v100
	v_exp_f32_e32 v128, v107
	v_sub_f32_e32 v107, v158, v98
	v_add_f32_e32 v100, v125, v100
	v_exp_f32_e32 v129, v107
	v_sub_f32_e32 v107, v159, v98
	v_add_f32_e32 v100, v126, v100
	v_exp_f32_e32 v146, v107
	v_sub_f32_e32 v107, v160, v98
	v_add_f32_e32 v100, v127, v100
	v_exp_f32_e32 v147, v107
	v_sub_f32_e32 v107, v161, v98
	v_add_f32_e32 v100, v128, v100
	v_exp_f32_e32 v152, v107
	v_sub_f32_e32 v107, v162, v98
	v_add_f32_e32 v100, v129, v100
	v_exp_f32_e32 v153, v107
	v_sub_f32_e32 v107, v163, v98
	v_add_f32_e32 v100, v146, v100
	v_exp_f32_e32 v154, v107
	v_sub_f32_e32 v107, v164, v98
	v_add_f32_e32 v100, v147, v100
	v_exp_f32_e32 v155, v107
	v_sub_f32_e32 v98, v165, v98
	v_add_f32_e32 v100, v152, v100
	v_exp_f32_e32 v156, v98
	v_add_f32_e32 v100, v153, v100
	v_add_f32_e32 v100, v154, v100
	v_add_f32_e32 v100, v155, v100
	v_add_f32_e32 v107, v156, v100
	v_cndmask_b32_e64 v98, v114, 1.0, s[6:7]
	v_fmac_f32_e32 v107, v214, v98
	v_cvt_pk_bf16_f32 v98, v99, v101
	v_cvt_pk_bf16_f32 v99, v113, v124
	v_cvt_pk_bf16_f32 v102, v102, v103
	v_cvt_pk_bf16_f32 v103, v104, v105
	v_cvt_pk_bf16_f32 v104, v109, v110
	v_cvt_pk_bf16_f32 v105, v111, v112
	ds_read_b64_tr_b16 v[110:111], v206 offset:16384
	ds_read_b64_tr_b16 v[112:113], v206 offset:20480
	ds_read_b64_tr_b16 v[160:161], v207 offset:16384
	ds_read_b64_tr_b16 v[162:163], v207 offset:20480
	ds_read_b64_tr_b16 v[220:221], v208 offset:16384
	ds_read_b64_tr_b16 v[222:223], v208 offset:20480
	ds_read_b64_tr_b16 v[224:225], v209 offset:16384
	ds_read_b64_tr_b16 v[226:227], v209 offset:20480
	ds_read_b64_tr_b16 v[232:233], v210 offset:16384
	ds_read_b64_tr_b16 v[234:235], v210 offset:20480
	ds_read_b64_tr_b16 v[236:237], v211 offset:16384
	ds_read_b64_tr_b16 v[238:239], v211 offset:20480
	ds_read_b64_tr_b16 v[240:241], v212 offset:16384
	ds_read_b64_tr_b16 v[242:243], v212 offset:20480
	v_cvt_pk_bf16_f32 v100, v125, v126
	v_cvt_pk_bf16_f32 v101, v127, v128
	s_waitcnt lgkmcnt(12)
; #define LDSP(T, p) ((__attribute__((address_space(3))) T*)(p))
; DI unsigned pack2(float lo, float hi) { unsigned r; asm("v_cvt_pk_bf16_f32 %0, %1, %2" : "=v"(r) : "v"(lo), "v"(hi)); return r; }
; template <int QS>
; DI void pv_tile(const char* Vs, const f32x4 (&s)[4][QS], f32x4 (&o)[QS][8], int lane) {
;   const int g = lane >> 4, i = lane & 15;
; #pragma unroll
;   for (int c = 0; c < 2; ++c) {
;     bf16x8 pf[QS];
; #pragma unroll
;     for (int qs = 0; qs < QS; ++qs) {
;       union { uint4 u; bf16x8 v; } cv;
;       cv.u.x = pack2(s[2 * c][qs][0], s[2 * c][qs][1]); cv.u.y = pack2(s[2 * c][qs][2], s[2 * c][qs][3]);
;       cv.u.z = pack2(s[2 * c + 1][qs][0], s[2 * c + 1][qs][1]); cv.u.w = pack2(s[2 * c + 1][qs][2], s[2 * c + 1][qs][3]);
;       pf[qs] = cv.v;
;     }
;     const int r1 = 32 * c + 4 * g + (i >> 2), r2 = r1 + 16;
; #pragma unroll
;     for (int dt = 0; dt < 8; ++dt) {
;       const s16x4 lo = __builtin_amdgcn_ds_read_tr16_b64_v4i16(LDSP(s16x4, Vs + r1 * 256 + ((dt ^ (r1 & 7)) << 5) + 8 * (i & 3)));
;       const s16x4 hi = __builtin_amdgcn_ds_read_tr16_b64_v4i16(LDSP(s16x4, Vs + r2 * 256 + ((dt ^ (r2 & 7)) << 5) + 8 * (i & 3)));
;       bf16x8 vf; vf[0] = lo[0]; vf[1] = lo[1]; vf[2] = lo[2]; vf[3] = lo[3]; vf[4] = hi[0]; vf[5] = hi[1]; vf[6] = hi[2]; vf[7] = hi[3];
; #pragma unroll
;       for (int qs = 0; qs < QS; ++qs) o[qs][dt] = __builtin_amdgcn_mfma_f32_16x16x32_bf16(vf, pf[qs], o[qs][dt], 0, 0, 0);
;     }
	v_mfma_f32_16x16x32_bf16 v[30:33], v[110:113], v[102:105], v[30:33]
	s_add_i32 s0, s30, -1
	s_and_b32 s30, s0, s30
	s_cmp_lg_u32 s30, 0
	v_mfma_f32_16x16x32_bf16 v[54:57], v[110:113], v[98:101], v[54:57]
	ds_read_b64_tr_b16 v[110:111], v213 offset:16384
	ds_read_b64_tr_b16 v[112:113], v213 offset:20480
	s_waitcnt lgkmcnt(12)
	v_mfma_f32_16x16x32_bf16 v[42:45], v[160:163], v[98:101], v[42:45]
	v_mfma_f32_16x16x32_bf16 v[26:29], v[160:163], v[102:105], v[26:29]
	ds_read_b64_tr_b16 v[160:161], v206 offset:24576
	ds_read_b64_tr_b16 v[162:163], v206 offset:28672
	s_waitcnt lgkmcnt(12)
	v_mfma_f32_16x16x32_bf16 v[46:49], v[220:223], v[98:101], v[46:49]
	v_mfma_f32_16x16x32_bf16 v[22:25], v[220:223], v[102:105], v[22:25]
	ds_read_b64_tr_b16 v[220:221], v207 offset:24576
	ds_read_b64_tr_b16 v[222:223], v207 offset:28672
	s_waitcnt lgkmcnt(12)
	v_mfma_f32_16x16x32_bf16 v[34:37], v[224:227], v[98:101], v[34:37]
	v_mfma_f32_16x16x32_bf16 v[18:21], v[224:227], v[102:105], v[18:21]
	ds_read_b64_tr_b16 v[224:225], v208 offset:24576
	ds_read_b64_tr_b16 v[226:227], v208 offset:28672
	s_waitcnt lgkmcnt(12)
	v_mfma_f32_16x16x32_bf16 v[38:41], v[232:235], v[98:101], v[38:41]
	v_mfma_f32_16x16x32_bf16 v[14:17], v[232:235], v[102:105], v[14:17]
	ds_read_b64_tr_b16 v[232:233], v209 offset:24576
	ds_read_b64_tr_b16 v[234:235], v209 offset:28672
	s_waitcnt lgkmcnt(12)
	v_mfma_f32_16x16x32_bf16 v[50:53], v[236:239], v[98:101], v[50:53]
	v_mfma_f32_16x16x32_bf16 v[10:13], v[236:239], v[102:105], v[10:13]
	ds_read_b64_tr_b16 v[236:237], v210 offset:24576
	ds_read_b64_tr_b16 v[238:239], v210 offset:28672
	s_waitcnt lgkmcnt(12)
	v_mfma_f32_16x16x32_bf16 v[58:61], v[240:243], v[98:101], v[58:61]
	v_mfma_f32_16x16x32_bf16 v[6:9], v[240:243], v[102:105], v[6:9]
	ds_read_b64_tr_b16 v[240:241], v211 offset:24576
	ds_read_b64_tr_b16 v[242:243], v211 offset:28672
	s_waitcnt lgkmcnt(12)
	v_mfma_f32_16x16x32_bf16 v[94:97], v[110:113], v[98:101], v[94:97]
	v_cvt_pk_bf16_f32 v98, v129, v146
	v_cvt_pk_bf16_f32 v99, v147, v152
	v_cvt_pk_bf16_f32 v100, v153, v154
	v_mfma_f32_16x16x32_bf16 v[2:5], v[110:113], v[102:105], v[2:5]
	ds_read_b64_tr_b16 v[110:111], v212 offset:24576
	ds_read_b64_tr_b16 v[112:113], v212 offset:28672
	v_cvt_pk_bf16_f32 v101, v155, v156
	v_cvt_pk_bf16_f32 v102, v116, v117
	v_cvt_pk_bf16_f32 v103, v118, v119
	v_cvt_pk_bf16_f32 v104, v120, v121
	v_cvt_pk_bf16_f32 v105, v122, v123
	s_waitcnt lgkmcnt(12)
	v_mfma_f32_16x16x32_bf16 v[54:57], v[160:163], v[98:101], v[54:57]
	v_mfma_f32_16x16x32_bf16 v[30:33], v[160:163], v[102:105], v[30:33]
	ds_read_b64_tr_b16 v[160:161], v213 offset:24576
	ds_read_b64_tr_b16 v[162:163], v213 offset:28672
	s_waitcnt lgkmcnt(12)
	v_mfma_f32_16x16x32_bf16 v[42:45], v[220:223], v[98:101], v[42:45]
	v_mfma_f32_16x16x32_bf16 v[26:29], v[220:223], v[102:105], v[26:29]
	s_waitcnt lgkmcnt(10)
	v_mfma_f32_16x16x32_bf16 v[46:49], v[224:227], v[98:101], v[46:49]
	v_mfma_f32_16x16x32_bf16 v[22:25], v[224:227], v[102:105], v[22:25]
	s_waitcnt lgkmcnt(8)
	v_mfma_f32_16x16x32_bf16 v[34:37], v[232:235], v[98:101], v[34:37]
	v_mfma_f32_16x16x32_bf16 v[18:21], v[232:235], v[102:105], v[18:21]
	s_waitcnt lgkmcnt(6)
	v_mfma_f32_16x16x32_bf16 v[38:41], v[236:239], v[98:101], v[38:41]
	v_mfma_f32_16x16x32_bf16 v[14:17], v[236:239], v[102:105], v[14:17]
	s_waitcnt lgkmcnt(4)
	v_mfma_f32_16x16x32_bf16 v[50:53], v[240:243], v[98:101], v[50:53]
	v_mfma_f32_16x16x32_bf16 v[10:13], v[240:243], v[102:105], v[10:13]
	s_waitcnt lgkmcnt(2)
	v_mfma_f32_16x16x32_bf16 v[58:61], v[110:113], v[98:101], v[58:61]
	v_mfma_f32_16x16x32_bf16 v[6:9], v[110:113], v[102:105], v[6:9]
	s_waitcnt lgkmcnt(0)
	v_mfma_f32_16x16x32_bf16 v[94:97], v[160:163], v[98:101], v[94:97]
	v_mfma_f32_16x16x32_bf16 v[2:5], v[160:163], v[102:105], v[2:5]
	s_cbranch_scc0 .LBB0_630
	v_mov_b32_e32 v216, v108
	v_mov_b32_e32 v166, v115
	v_mov_b32_e32 v215, v106
	v_mov_b32_e32 v214, v107
	s_branch .LBB0_616

; DI void load_tile_k(int tid, const bf16_t* __restrict__ g, int ld, char* dst) { u32x4 r[4]; ldg_tile(tid, g, ld, r); sts_tile_k(tid, r, dst); }
; DI void load_tile_v(int tid, const bf16_t* __restrict__ g, int ld, char* dst) { u32x4 r[4]; ldg_tile(tid, g, ld, r); sts_tile_v(tid, r, dst); }
; DI void ldg_tile(int tid, const bf16_t* __restrict__ g, int ld, u32x4 (&r)[4]) {
; #pragma unroll
;   for (int i = 0; i < 4; ++i) { const int idx = tid + 256 * i, row = idx >> 4, ch = idx & 15; r[i] = *(const u32x4*)(g + (size_t)row * ld + ch * 8); }
; }
; DI void sts_tile_k(int tid, const u32x4 (&r)[4], char* dst) {
; #pragma unroll
;   for (int i = 0; i < 4; ++i) { const int idx = tid + 256 * i, row = idx >> 4, ch = idx & 15; *(u32x4*)(dst + koff(row, ch)) = r[i]; }
; }
; DI void sts_tile_v(int tid, const u32x4 (&r)[4], char* dst) {
; #pragma unroll
;   for (int i = 0; i < 4; ++i) { const int idx = tid + 256 * i, row = idx >> 4, ch = idx & 15; *(u32x4*)(dst + voff(row, ch)) = r[i]; }
; }
; DI void ldg_tile_k2(int tid, const bf16_t* __restrict__ g, int ld, u32x4 (&r)[2]) {
; #pragma unroll
;   for (int i = 0; i < 2; ++i) { const int idx = tid + 256 * i, row = idx >> 3, ch = idx & 7; r[i] = *(const u32x4*)(g + (size_t)row * ld + ch * 8); }
; }
; DI void sts_tile_k2(int tid, const u32x4 (&r)[2], char* dst) {
; #pragma unroll
;   for (int i = 0; i < 2; ++i) { const int idx = tid + 256 * i, row = idx >> 3, ch = idx & 7; *(u32x4*)(dst + k2off(row, ch)) = r[i]; }
; }
; template <int QS>
; DI void mla_attn_item(int item, const bf16_t* __restrict__ q, const bf16_t* __restrict__ kv, const bf16_t* __restrict__ krope,
;                               const int* __restrict__ pos, bf16_t* __restrict__ mix, char* smem) {
;     ...
;     __syncthreads();
;     load_tile_k(tid, kv + (tb + j * 64) * 2048 + h * 256, 2048, Ks);
;     load_tile_v(tid, kv + (tb + j * 64) * 2048 + h * 256 + 128, 2048, Vs);
;     { u32x4 r2[2]; ldg_tile_k2(tid, krope + (tb + j * 64) * 64, 64, r2); sts_tile_k2(tid, r2, K2s); }
;     __syncthreads();
.LBB0_965:
	v_lshl_add_u64 v[2:3], s[90:91], 0, v[174:175]
	s_mov_b32 s0, 0x2e120000
	v_add_co_u32_e32 v2, vcc, s0, v2
	v_lshl_add_u64 v[120:121], s[90:91], 0, v[172:173]
	s_nop 0
	v_addc_co_u32_e32 v3, vcc, 0, v3, vcc
	v_add_co_u32_e32 v132, vcc, s0, v120
	v_lshl_add_u64 v[124:125], s[90:91], 0, v[170:171]
	s_nop 0
	v_addc_co_u32_e32 v133, vcc, 0, v121, vcc
	v_add_co_u32_e32 v134, vcc, s0, v124
	s_barrier
	global_load_dwordx4 v[116:119], v[2:3], off
	global_load_dwordx4 v[120:123], v[132:133], off
	v_addc_co_u32_e32 v135, vcc, 0, v125, vcc
	v_lshl_add_u64 v[128:129], s[90:91], 0, v[168:169]
	v_add_co_u32_e32 v136, vcc, s0, v128
	global_load_dwordx4 v[124:127], v[134:135], off
	s_nop 0
	v_addc_co_u32_e32 v137, vcc, 0, v129, vcc
	global_load_dwordx4 v[128:131], v[136:137], off
	global_load_dwordx4 v[138:141], v[2:3], off offset:256
	global_load_dwordx4 v[142:145], v[132:133], off offset:256
	global_load_dwordx4 v[176:179], v[134:135], off offset:256
	global_load_dwordx4 v[180:183], v[136:137], off offset:256
	v_lshl_add_u64 v[146:147], s[90:91], 0, v[164:165]
	global_load_dwordx4 v[184:187], v[146:147], off
	v_lshl_add_u64 v[238:239], s[90:91], 0, v[166:167]
	global_load_dwordx4 v[234:237], v[238:239], off
	s_add_i32 s0, s5, 63
	s_cmp_le_i32 s0, s14
	s_cselect_b64 s[8:9], -1, 0
	s_mov_b64 s[0:1], -1
	s_and_b64 vcc, exec, s[8:9]
	s_waitcnt vmcnt(9)
	ds_write_b128 v206, v[116:119]
	s_waitcnt vmcnt(8)
	ds_write_b128 v207, v[120:123]
	s_waitcnt vmcnt(7)
	ds_write_b128 v208, v[124:127]
	s_waitcnt vmcnt(6)
	ds_write_b128 v209, v[128:131]
	s_nop 0
	s_waitcnt vmcnt(5)
	ds_write_b128 v210, v[138:141] offset:16384
	s_waitcnt vmcnt(4)
	ds_write_b128 v211, v[142:145] offset:16384
	s_waitcnt vmcnt(3)
	ds_write_b128 v212, v[176:179] offset:16384
	s_waitcnt vmcnt(2)
	ds_write_b128 v213, v[180:183] offset:16384
	s_nop 0
	s_waitcnt vmcnt(1)
	ds_write_b128 v214, v[184:187] offset:32768
	s_waitcnt vmcnt(0)
	ds_write_b128 v215, v[234:237] offset:32768
	s_waitcnt lgkmcnt(0)
	s_barrier
; template <int NKS, int QS>
; DI void qk_tile(const char* Ks, const bf16x8 (&qf)[QS][6], int ks0, f32x4 (&s)[4][QS], int lane) {
; #pragma unroll
;   for (int ks = 0; ks < NKS; ++ks)
; #pragma unroll
;     for (int kt = 0; kt < 4; ++kt) {
;       const bf16x8 kf = *(const bf16x8*)(Ks + koff(kt * 16 + (lane & 15), ks * 4 + (lane >> 4)));
; #pragma unroll
;       for (int qs = 0; qs < QS; ++qs) s[kt][qs] = __builtin_amdgcn_mfma_f32_16x16x32_bf16(kf, qf[qs][ks0 + ks], s[kt][qs], 0, 0, 0);
;     }
; }
; template <int QS>
; DI void qk_tile2(const char* K2s, const bf16x8 (&qf)[QS][6], f32x4 (&s)[4][QS], int lane) {
; #pragma unroll
;   for (int ks = 0; ks < 2; ++ks)
; #pragma unroll
;     for (int kt = 0; kt < 4; ++kt) {
;       const bf16x8 kf = *(const bf16x8*)(K2s + k2off(kt * 16 + (lane & 15), ks * 4 + (lane >> 4)));
; #pragma unroll
;       for (int qs = 0; qs < QS; ++qs) s[kt][qs] = __builtin_amdgcn_mfma_f32_16x16x32_bf16(kf, qf[qs][4 + ks], s[kt][qs], 0, 0, 0);
;     }
; }
	ds_read_b128 v[176:179], v216
	ds_read_b128 v[180:183], v216 offset:4096
	ds_read_b128 v[184:187], v217
	ds_read_b128 v[234:237], v216 offset:8192
	ds_read_b128 v[238:241], v216 offset:12288
	s_waitcnt lgkmcnt(4)
	v_mfma_f32_16x16x32_bf16 v[144:147], v[176:179], v[4:7], 0
	v_mfma_f32_16x16x32_bf16 v[128:131], v[176:179], v[20:23], 0
	ds_read_b128 v[176:179], v217 offset:4096
	s_waitcnt lgkmcnt(4)
	v_mfma_f32_16x16x32_bf16 v[140:143], v[180:183], v[4:7], 0
	v_mfma_f32_16x16x32_bf16 v[124:127], v[180:183], v[20:23], 0
	ds_read_b128 v[180:183], v217 offset:8192
	s_waitcnt lgkmcnt(4)
	v_mfma_f32_16x16x32_bf16 v[144:147], v[184:187], v[8:11], v[144:147]
	v_mfma_f32_16x16x32_bf16 v[128:131], v[184:187], v[24:27], v[128:131]
	ds_read_b128 v[184:187], v217 offset:12288
	s_waitcnt lgkmcnt(4)
	v_mfma_f32_16x16x32_bf16 v[136:139], v[234:237], v[4:7], 0
	v_mfma_f32_16x16x32_bf16 v[120:123], v[234:237], v[20:23], 0
	ds_read_b128 v[234:237], v218
	s_waitcnt lgkmcnt(4)
	v_mfma_f32_16x16x32_bf16 v[132:135], v[238:241], v[4:7], 0
	v_mfma_f32_16x16x32_bf16 v[116:119], v[238:241], v[20:23], 0
	ds_read_b128 v[238:241], v218 offset:4096
	s_waitcnt lgkmcnt(4)
	v_mfma_f32_16x16x32_bf16 v[140:143], v[176:179], v[8:11], v[140:143]
	v_mfma_f32_16x16x32_bf16 v[124:127], v[176:179], v[24:27], v[124:127]
	ds_read_b128 v[176:179], v218 offset:8192
	s_waitcnt lgkmcnt(4)
	v_mfma_f32_16x16x32_bf16 v[136:139], v[180:183], v[8:11], v[136:139]
	v_mfma_f32_16x16x32_bf16 v[120:123], v[180:183], v[24:27], v[120:123]
	ds_read_b128 v[180:183], v218 offset:12288
	s_waitcnt lgkmcnt(4)
	v_mfma_f32_16x16x32_bf16 v[132:135], v[184:187], v[8:11], v[132:135]
	v_mfma_f32_16x16x32_bf16 v[116:119], v[184:187], v[24:27], v[116:119]
	ds_read_b128 v[184:187], v219
	s_waitcnt lgkmcnt(4)
	v_mfma_f32_16x16x32_bf16 v[144:147], v[234:237], v[12:15], v[144:147]
	v_mfma_f32_16x16x32_bf16 v[128:131], v[234:237], v[28:31], v[128:131]
	ds_read_b128 v[234:237], v219 offset:4096
	s_waitcnt lgkmcnt(4)
	v_mfma_f32_16x16x32_bf16 v[140:143], v[238:241], v[12:15], v[140:143]
	v_mfma_f32_16x16x32_bf16 v[124:127], v[238:241], v[28:31], v[124:127]
	ds_read_b128 v[238:241], v219 offset:8192
	s_waitcnt lgkmcnt(4)
	v_mfma_f32_16x16x32_bf16 v[136:139], v[176:179], v[12:15], v[136:139]
	v_mfma_f32_16x16x32_bf16 v[120:123], v[176:179], v[28:31], v[120:123]
	ds_read_b128 v[176:179], v219 offset:12288
	s_waitcnt lgkmcnt(4)
	v_mfma_f32_16x16x32_bf16 v[132:135], v[180:183], v[12:15], v[132:135]
	v_mfma_f32_16x16x32_bf16 v[116:119], v[180:183], v[28:31], v[116:119]
	ds_read_b128 v[180:183], v220 offset:32768
	s_waitcnt lgkmcnt(4)
	v_mfma_f32_16x16x32_bf16 v[144:147], v[184:187], v[16:19], v[144:147]
	v_mfma_f32_16x16x32_bf16 v[128:131], v[184:187], v[32:35], v[128:131]
	ds_read_b128 v[184:187], v220 offset:34816
	s_waitcnt lgkmcnt(4)
	v_mfma_f32_16x16x32_bf16 v[140:143], v[234:237], v[16:19], v[140:143]
	v_mfma_f32_16x16x32_bf16 v[124:127], v[234:237], v[32:35], v[124:127]
	ds_read_b128 v[234:237], v220 offset:36864
	s_waitcnt lgkmcnt(4)
	v_mfma_f32_16x16x32_bf16 v[136:139], v[238:241], v[16:19], v[136:139]
	v_mfma_f32_16x16x32_bf16 v[120:123], v[238:241], v[32:35], v[120:123]
	ds_read_b128 v[238:241], v220 offset:38912
	s_waitcnt lgkmcnt(4)
	v_mfma_f32_16x16x32_bf16 v[132:135], v[176:179], v[16:19], v[132:135]
	v_mfma_f32_16x16x32_bf16 v[116:119], v[176:179], v[32:35], v[116:119]
	ds_read_b128 v[176:179], v221 offset:32768
	s_waitcnt lgkmcnt(4)
	v_mfma_f32_16x16x32_bf16 v[144:147], v[180:183], v[36:39], v[144:147]
	v_mfma_f32_16x16x32_bf16 v[128:131], v[180:183], v[40:43], v[128:131]
	ds_read_b128 v[180:183], v221 offset:34816
	s_waitcnt lgkmcnt(4)
	v_mfma_f32_16x16x32_bf16 v[140:143], v[184:187], v[36:39], v[140:143]
	v_mfma_f32_16x16x32_bf16 v[124:127], v[184:187], v[40:43], v[124:127]
	ds_read_b128 v[184:187], v221 offset:36864
	s_waitcnt lgkmcnt(4)
	v_mfma_f32_16x16x32_bf16 v[136:139], v[234:237], v[36:39], v[136:139]
	v_mfma_f32_16x16x32_bf16 v[120:123], v[234:237], v[40:43], v[120:123]
	ds_read_b128 v[234:237], v221 offset:38912
	s_waitcnt lgkmcnt(4)
	v_mfma_f32_16x16x32_bf16 v[132:135], v[238:241], v[36:39], v[132:135]
	v_mfma_f32_16x16x32_bf16 v[116:119], v[238:241], v[40:43], v[116:119]
	s_waitcnt lgkmcnt(3)
	v_mfma_f32_16x16x32_bf16 v[144:147], v[176:179], v[44:47], v[144:147]
	v_mfma_f32_16x16x32_bf16 v[128:131], v[176:179], v[48:51], v[128:131]
	s_waitcnt lgkmcnt(2)
	v_mfma_f32_16x16x32_bf16 v[140:143], v[180:183], v[44:47], v[140:143]
	v_mfma_f32_16x16x32_bf16 v[124:127], v[180:183], v[48:51], v[124:127]
	s_waitcnt lgkmcnt(1)
	v_mfma_f32_16x16x32_bf16 v[136:139], v[184:187], v[44:47], v[136:139]
	v_mfma_f32_16x16x32_bf16 v[120:123], v[184:187], v[48:51], v[120:123]
	s_waitcnt lgkmcnt(0)
	v_mfma_f32_16x16x32_bf16 v[132:135], v[234:237], v[44:47], v[132:135]
	v_mfma_f32_16x16x32_bf16 v[116:119], v[234:237], v[48:51], v[116:119]
	s_nop 7
	s_cbranch_vccz .LBB0_967
	s_nop 0
	v_pk_fma_f32 v[178:179], v[144:145], s[70:71], 0 op_sel_hi:[1,0,0]
	v_pk_fma_f32 v[2:3], v[146:147], s[70:71], 0 op_sel_hi:[1,0,0]
	v_max3_f32 v176, v178, s83, v179
	v_max3_f32 v176, v176, v2, v3
	v_pk_fma_f32 v[180:181], v[140:141], s[70:71], 0 op_sel_hi:[1,0,0]
	s_mov_b64 s[0:1], 0
	v_max3_f32 v182, v176, v180, v181
	v_pk_fma_f32 v[176:177], v[142:143], s[70:71], 0 op_sel_hi:[1,0,0]
	s_nop 0
	v_max3_f32 v184, v182, v176, v177
	v_pk_fma_f32 v[182:183], v[136:137], s[70:71], 0 op_sel_hi:[1,0,0]
	s_nop 0
	v_max3_f32 v186, v184, v182, v183
	v_pk_fma_f32 v[184:185], v[138:139], s[70:71], 0 op_sel_hi:[1,0,0]
	s_nop 0
	v_max3_f32 v188, v186, v184, v185
	v_pk_fma_f32 v[186:187], v[132:133], s[70:71], 0 op_sel_hi:[1,0,0]
	s_nop 0
	v_max3_f32 v230, v188, v186, v187
	v_pk_fma_f32 v[188:189], v[134:135], s[70:71], 0 op_sel_hi:[1,0,0]
	s_nop 0
	v_max3_f32 v230, v230, v188, v189

; #define LDSP(T, p) ((__attribute__((address_space(3))) T*)(p))
; DI unsigned pack2(float lo, float hi) { unsigned r; asm("v_cvt_pk_bf16_f32 %0, %1, %2" : "=v"(r) : "v"(lo), "v"(hi)); return r; }
; template <int QS>
; DI void pv_tile(const char* Vs, const f32x4 (&s)[4][QS], f32x4 (&o)[QS][8], int lane) {
;   const int g = lane >> 4, i = lane & 15;
; #pragma unroll
;   for (int c = 0; c < 2; ++c) {
;     bf16x8 pf[QS];
; #pragma unroll
;     for (int qs = 0; qs < QS; ++qs) {
;       union { uint4 u; bf16x8 v; } cv;
;       cv.u.x = pack2(s[2 * c][qs][0], s[2 * c][qs][1]); cv.u.y = pack2(s[2 * c][qs][2], s[2 * c][qs][3]);
;       cv.u.z = pack2(s[2 * c + 1][qs][0], s[2 * c + 1][qs][1]); cv.u.w = pack2(s[2 * c + 1][qs][2], s[2 * c + 1][qs][3]);
;       pf[qs] = cv.v;
;     }
;     const int r1 = 32 * c + 4 * g + (i >> 2), r2 = r1 + 16;
; #pragma unroll
;     for (int dt = 0; dt < 8; ++dt) {
;       const s16x4 lo = __builtin_amdgcn_ds_read_tr16_b64_v4i16(LDSP(s16x4, Vs + r1 * 256 + ((dt ^ (r1 & 7)) << 5) + 8 * (i & 3)));
;       const s16x4 hi = __builtin_amdgcn_ds_read_tr16_b64_v4i16(LDSP(s16x4, Vs + r2 * 256 + ((dt ^ (r2 & 7)) << 5) + 8 * (i & 3)));
;       bf16x8 vf; vf[0] = lo[0]; vf[1] = lo[1]; vf[2] = lo[2]; vf[3] = lo[3]; vf[4] = hi[0]; vf[5] = hi[1]; vf[6] = hi[2]; vf[7] = hi[3];
; #pragma unroll
;       for (int qs = 0; qs < QS; ++qs) o[qs][dt] = __builtin_amdgcn_mfma_f32_16x16x32_bf16(vf, pf[qs], o[qs][dt], 0, 0, 0);
;     }
; template <int MODE, int QS>
; DI void softmax_tile(f32x4 (&s)[4][QS], f32x4 (&o)[QS][8], float (&m)[QS], float (&l)[QS], const int (&qi)[QS], const unsigned (&qmask)[QS],
;                      int kbase, int tilebit, float sc, int lane, bool interior) {
;     ...
;     mx = fmaxf(mx, __shfl_xor(mx, 16)); mx = fmaxf(mx, __shfl_xor(mx, 32));
;     const bool keep = __all(mx - m[qs] <= 23.0831f);
;     const float mn = keep ? m[qs] : fmaxf(m[qs], mx);
;     const float alpha = keep ? 1.f : __builtin_amdgcn_exp2f(m[qs] - mn);
;     m[qs] = mn;
;     const float mnc = fmaxf(mn, -1e20f);
;     float ps = 0.f;
; #pragma unroll
;     for (int kt = 0; kt < 4; ++kt)
; #pragma unroll
;       for (int r = 0; r < 4; ++r) { const float p = __builtin_amdgcn_exp2f(s[kt][qs][r] - mnc); s[kt][qs][r] = p; ps += p; }
;     l[qs] = l[qs] * alpha + ps;
;     if (!keep) {
; #pragma unroll
;       for (int dt = 0; dt < 8; ++dt) o[qs][dt] *= alpha;
;     }
.LBB0_977:
	v_max_f32_e32 v117, v124, v124
	v_max_f32_e32 v117, 0xe0ad78ec, v117
	v_sub_f32_e32 v118, v136, v117
	v_exp_f32_e32 v120, v118
	v_sub_f32_e32 v119, v137, v117
	v_exp_f32_e32 v121, v119
	v_sub_f32_e32 v119, v132, v117
	v_exp_f32_e32 v122, v119
	v_sub_f32_e32 v119, v133, v117
	v_exp_f32_e32 v123, v119
	v_sub_f32_e32 v119, v138, v117
	v_add_f32_e32 v118, 0, v120
	v_exp_f32_e32 v126, v119
	v_sub_f32_e32 v119, v139, v117
	v_add_f32_e32 v118, v121, v118
	v_exp_f32_e32 v127, v119
	v_sub_f32_e32 v119, v134, v117
	v_add_f32_e32 v118, v122, v118
	v_exp_f32_e32 v128, v119
	v_sub_f32_e32 v119, v135, v117
	v_add_f32_e32 v118, v123, v118
	v_exp_f32_e32 v129, v119
	v_sub_f32_e32 v119, v140, v117
	v_add_f32_e32 v118, v126, v118
	v_exp_f32_e32 v130, v119
	v_sub_f32_e32 v119, v141, v117
	v_add_f32_e32 v118, v127, v118
	v_exp_f32_e32 v131, v119
	v_sub_f32_e32 v119, v142, v117
	v_add_f32_e32 v118, v128, v118
	v_exp_f32_e32 v132, v119
	v_sub_f32_e32 v119, v143, v117
	v_add_f32_e32 v118, v129, v118
	v_exp_f32_e32 v133, v119
	v_sub_f32_e32 v119, v144, v117
	v_add_f32_e32 v118, v130, v118
	v_exp_f32_e32 v134, v119
	v_sub_f32_e32 v119, v145, v117
	v_add_f32_e32 v118, v131, v118
	v_exp_f32_e32 v135, v119
	v_sub_f32_e32 v119, v146, v117
	v_add_f32_e32 v118, v132, v118
	v_exp_f32_e32 v136, v119
	v_sub_f32_e32 v117, v147, v117
	v_add_f32_e32 v118, v133, v118
	v_exp_f32_e32 v137, v117
	v_add_f32_e32 v118, v134, v118
	v_add_f32_e32 v118, v135, v118
	v_add_f32_e32 v118, v136, v118
	v_add_f32_e32 v125, v137, v118
	v_cndmask_b32_e64 v116, v116, 1.0, s[0:1]
	v_fmac_f32_e32 v125, v232, v116
	v_max_f32_e32 v116, v230, v230
	v_max_f32_e32 v116, 0xe0ad78ec, v116
	v_sub_f32_e32 v117, v178, v116
	v_exp_f32_e32 v117, v117
	v_sub_f32_e32 v119, v179, v116
	v_exp_f32_e32 v119, v119
	v_sub_f32_e32 v2, v2, v116
	v_exp_f32_e32 v138, v2
	v_add_f32_e32 v118, 0, v117
	v_add_f32_e32 v118, v119, v118
	v_sub_f32_e32 v3, v3, v116
	v_add_f32_e32 v2, v138, v118
	v_exp_f32_e32 v3, v3
	v_sub_f32_e32 v118, v180, v116
	v_cvt_pk_bf16_f32 v120, v120, v121
	v_cvt_pk_bf16_f32 v121, v122, v123
	v_cvt_pk_bf16_f32 v122, v126, v127
	v_cvt_pk_bf16_f32 v123, v128, v129
	ds_read_b64_tr_b16 v[126:127], v222 offset:16384
	ds_read_b64_tr_b16 v[128:129], v222 offset:20480
	ds_read_b64_tr_b16 v[232:233], v223 offset:16384
	ds_read_b64_tr_b16 v[234:235], v223 offset:20480
	ds_read_b64_tr_b16 v[236:237], v224 offset:16384
	ds_read_b64_tr_b16 v[238:239], v224 offset:20480
	ds_read_b64_tr_b16 v[240:241], v225 offset:16384
	ds_read_b64_tr_b16 v[242:243], v225 offset:20480
	v_exp_f32_e32 v118, v118
	v_add_f32_e32 v2, v3, v2
	v_sub_f32_e32 v139, v181, v116
	v_sub_f32_e32 v140, v176, v116
	v_sub_f32_e32 v141, v177, v116
	v_sub_f32_e32 v142, v182, v116
	v_sub_f32_e32 v143, v183, v116
	v_sub_f32_e32 v144, v184, v116
	v_sub_f32_e32 v145, v185, v116
	v_sub_f32_e32 v146, v186, v116
	v_sub_f32_e32 v147, v187, v116
	v_sub_f32_e32 v176, v188, v116
	v_sub_f32_e32 v116, v189, v116
	v_add_f32_e32 v2, v118, v2
	v_exp_f32_e32 v139, v139
	v_exp_f32_e32 v140, v140
	v_exp_f32_e32 v141, v141
	v_exp_f32_e32 v177, v116
	v_cvt_pk_bf16_f32 v116, v117, v119
	v_cvt_pk_bf16_f32 v117, v138, v3
	v_cvt_pk_bf16_f32 v118, v118, v139
	v_cvt_pk_bf16_f32 v119, v140, v141
	s_waitcnt lgkmcnt(6)
	v_mfma_f32_16x16x32_bf16 v[56:59], v[126:129], v[120:123], v[56:59]
	v_exp_f32_e32 v142, v142
	v_exp_f32_e32 v143, v143
	v_exp_f32_e32 v144, v144
	v_mfma_f32_16x16x32_bf16 v[84:87], v[126:129], v[116:119], v[84:87]
	ds_read_b64_tr_b16 v[126:127], v226 offset:16384
	ds_read_b64_tr_b16 v[128:129], v226 offset:20480
	v_exp_f32_e32 v145, v145
	v_exp_f32_e32 v146, v146
	s_waitcnt lgkmcnt(6)
	v_mfma_f32_16x16x32_bf16 v[80:83], v[232:235], v[116:119], v[80:83]
	v_exp_f32_e32 v147, v147
	v_exp_f32_e32 v176, v176
	v_add_f32_e32 v2, v139, v2
	v_mfma_f32_16x16x32_bf16 v[52:55], v[232:235], v[120:123], v[52:55]
	ds_read_b64_tr_b16 v[232:233], v227 offset:16384
	ds_read_b64_tr_b16 v[234:235], v227 offset:20480
	v_add_f32_e32 v2, v140, v2
	v_add_f32_e32 v2, v141, v2
	s_waitcnt lgkmcnt(6)
; #define LDSP(T, p) ((__attribute__((address_space(3))) T*)(p))
; DI unsigned pack2(float lo, float hi) { unsigned r; asm("v_cvt_pk_bf16_f32 %0, %1, %2" : "=v"(r) : "v"(lo), "v"(hi)); return r; }
; template <int QS>
; DI void pv_tile(const char* Vs, const f32x4 (&s)[4][QS], f32x4 (&o)[QS][8], int lane) {
;   const int g = lane >> 4, i = lane & 15;
; #pragma unroll
;   for (int c = 0; c < 2; ++c) {
;     bf16x8 pf[QS];
; #pragma unroll
;     for (int qs = 0; qs < QS; ++qs) {
;       union { uint4 u; bf16x8 v; } cv;
;       cv.u.x = pack2(s[2 * c][qs][0], s[2 * c][qs][1]); cv.u.y = pack2(s[2 * c][qs][2], s[2 * c][qs][3]);
;       cv.u.z = pack2(s[2 * c + 1][qs][0], s[2 * c + 1][qs][1]); cv.u.w = pack2(s[2 * c + 1][qs][2], s[2 * c + 1][qs][3]);
;       pf[qs] = cv.v;
;     }
;     const int r1 = 32 * c + 4 * g + (i >> 2), r2 = r1 + 16;
; #pragma unroll
;     for (int dt = 0; dt < 8; ++dt) {
;       const s16x4 lo = __builtin_amdgcn_ds_read_tr16_b64_v4i16(LDSP(s16x4, Vs + r1 * 256 + ((dt ^ (r1 & 7)) << 5) + 8 * (i & 3)));
;       const s16x4 hi = __builtin_amdgcn_ds_read_tr16_b64_v4i16(LDSP(s16x4, Vs + r2 * 256 + ((dt ^ (r2 & 7)) << 5) + 8 * (i & 3)));
;       bf16x8 vf; vf[0] = lo[0]; vf[1] = lo[1]; vf[2] = lo[2]; vf[3] = lo[3]; vf[4] = hi[0]; vf[5] = hi[1]; vf[6] = hi[2]; vf[7] = hi[3];
; #pragma unroll
;       for (int qs = 0; qs < QS; ++qs) o[qs][dt] = __builtin_amdgcn_mfma_f32_16x16x32_bf16(vf, pf[qs], o[qs][dt], 0, 0, 0);
;     }
	v_mfma_f32_16x16x32_bf16 v[88:91], v[236:239], v[116:119], v[88:91]
	v_add_f32_e32 v2, v142, v2
	v_add_f32_e32 v2, v143, v2
	v_add_f32_e32 v2, v144, v2
	v_mfma_f32_16x16x32_bf16 v[60:63], v[236:239], v[120:123], v[60:63]
	ds_read_b64_tr_b16 v[236:237], v228 offset:16384
	ds_read_b64_tr_b16 v[238:239], v228 offset:20480
	v_add_f32_e32 v2, v145, v2
	v_add_f32_e32 v2, v146, v2
	s_waitcnt lgkmcnt(6)
	v_mfma_f32_16x16x32_bf16 v[92:95], v[240:243], v[116:119], v[92:95]
	v_add_f32_e32 v2, v147, v2
	v_add_f32_e32 v2, v176, v2
	v_add_f32_e32 v2, v177, v2
	v_mfma_f32_16x16x32_bf16 v[64:67], v[240:243], v[120:123], v[64:67]
	ds_read_b64_tr_b16 v[240:241], v229 offset:16384
	ds_read_b64_tr_b16 v[242:243], v229 offset:20480
	v_cndmask_b32_e64 v0, v0, 1.0, s[6:7]
	s_add_i32 s15, s15, -1
	s_waitcnt lgkmcnt(6)
	v_mfma_f32_16x16x32_bf16 v[96:99], v[126:129], v[116:119], v[96:99]
	s_add_i32 s5, s5, 64
	s_mov_b64 s[0:1], 0x2000
	v_fmac_f32_e32 v2, v231, v0
	v_mfma_f32_16x16x32_bf16 v[68:71], v[126:129], v[120:123], v[68:71]
	ds_read_b64_tr_b16 v[126:127], v222 offset:24576
	ds_read_b64_tr_b16 v[128:129], v222 offset:28672
	v_lshl_add_u64 v[164:165], v[164:165], 0, s[0:1]
	v_lshl_add_u64 v[166:167], v[166:167], 0, s[0:1]
	s_waitcnt lgkmcnt(6)
	v_mfma_f32_16x16x32_bf16 v[100:103], v[232:235], v[116:119], v[100:103]
	v_lshl_add_u64 v[168:169], v[168:169], 0, s[18:19]
	v_lshl_add_u64 v[170:171], v[170:171], 0, s[18:19]
	v_lshl_add_u64 v[172:173], v[172:173], 0, s[18:19]
	v_mfma_f32_16x16x32_bf16 v[72:75], v[232:235], v[120:123], v[72:75]
	ds_read_b64_tr_b16 v[232:233], v223 offset:24576
	ds_read_b64_tr_b16 v[234:235], v223 offset:28672
	v_lshl_add_u64 v[174:175], v[174:175], 0, s[18:19]
	s_cmp_lg_u32 s15, 0
	s_waitcnt lgkmcnt(6)
	v_mfma_f32_16x16x32_bf16 v[104:107], v[236:239], v[116:119], v[104:107]
	v_mfma_f32_16x16x32_bf16 v[76:79], v[236:239], v[120:123], v[76:79]
	ds_read_b64_tr_b16 v[236:237], v224 offset:24576
	ds_read_b64_tr_b16 v[238:239], v224 offset:28672
	s_waitcnt lgkmcnt(6)
	v_mfma_f32_16x16x32_bf16 v[112:115], v[240:243], v[116:119], v[112:115]
	v_cvt_pk_bf16_f32 v116, v130, v131
	v_cvt_pk_bf16_f32 v117, v132, v133
	v_cvt_pk_bf16_f32 v118, v134, v135
	v_mfma_f32_16x16x32_bf16 v[108:111], v[240:243], v[120:123], v[108:111]
	ds_read_b64_tr_b16 v[240:241], v225 offset:24576
	ds_read_b64_tr_b16 v[242:243], v225 offset:28672
	v_cvt_pk_bf16_f32 v120, v142, v143
	v_cvt_pk_bf16_f32 v121, v144, v145
	v_cvt_pk_bf16_f32 v122, v146, v147
	v_cvt_pk_bf16_f32 v123, v176, v177
	v_cvt_pk_bf16_f32 v119, v136, v137
	s_waitcnt lgkmcnt(6)
	v_mfma_f32_16x16x32_bf16 v[84:87], v[126:129], v[120:123], v[84:87]
	v_mfma_f32_16x16x32_bf16 v[56:59], v[126:129], v[116:119], v[56:59]
	ds_read_b64_tr_b16 v[126:127], v226 offset:24576
	ds_read_b64_tr_b16 v[128:129], v226 offset:28672
	s_waitcnt lgkmcnt(6)
	v_mfma_f32_16x16x32_bf16 v[80:83], v[232:235], v[120:123], v[80:83]
	v_mfma_f32_16x16x32_bf16 v[52:55], v[232:235], v[116:119], v[52:55]
	ds_read_b64_tr_b16 v[232:233], v227 offset:24576
	ds_read_b64_tr_b16 v[234:235], v227 offset:28672
	s_waitcnt lgkmcnt(6)
	v_mfma_f32_16x16x32_bf16 v[88:91], v[236:239], v[120:123], v[88:91]
	v_mfma_f32_16x16x32_bf16 v[60:63], v[236:239], v[116:119], v[60:63]
	ds_read_b64_tr_b16 v[236:237], v228 offset:24576
	ds_read_b64_tr_b16 v[238:239], v228 offset:28672
	s_waitcnt lgkmcnt(6)
	v_mfma_f32_16x16x32_bf16 v[92:95], v[240:243], v[120:123], v[92:95]
	v_mfma_f32_16x16x32_bf16 v[64:67], v[240:243], v[116:119], v[64:67]
	ds_read_b64_tr_b16 v[240:241], v229 offset:24576
	ds_read_b64_tr_b16 v[242:243], v229 offset:28672
	s_waitcnt lgkmcnt(6)
	v_mfma_f32_16x16x32_bf16 v[96:99], v[126:129], v[120:123], v[96:99]
	v_mfma_f32_16x16x32_bf16 v[68:71], v[126:129], v[116:119], v[68:71]
	s_waitcnt lgkmcnt(4)
	v_mfma_f32_16x16x32_bf16 v[100:103], v[232:235], v[120:123], v[100:103]
	v_mfma_f32_16x16x32_bf16 v[72:75], v[232:235], v[116:119], v[72:75]
	s_waitcnt lgkmcnt(2)
	v_mfma_f32_16x16x32_bf16 v[104:107], v[236:239], v[120:123], v[104:107]
	v_mfma_f32_16x16x32_bf16 v[76:79], v[236:239], v[116:119], v[76:79]
	s_waitcnt lgkmcnt(0)
	v_mfma_f32_16x16x32_bf16 v[112:115], v[240:243], v[120:123], v[112:115]
	v_mfma_f32_16x16x32_bf16 v[108:111], v[240:243], v[116:119], v[108:111]
	s_cbranch_scc0 .LBB0_961
	v_mov_b32_e32 v233, v124
	v_mov_b32_e32 v0, v230
	v_mov_b32_e32 v232, v125
	v_mov_b32_e32 v231, v2
	s_branch .LBB0_965
